# v26: v25 + hand-scheduled layer-A input-projection v-tile epilogue (four interleaved gelu chains, no dependent-op nops, the eight rows' LayerNorm partial sums reduced across lanes in one batch, rinv l
# speedup vs baseline: 1.0082x; 1.0051x over previous
.LBB0_452:
	v_lshlrev_b32_e32 v144, 2, v142
	global_load_dword v200, v144, s[16:17]
	global_load_dword v202, v144, s[16:17] offset:64
	global_load_dword v204, v144, s[16:17] offset:128
	global_load_dword v206, v144, s[16:17] offset:192
	global_load_dword v208, v144, s[16:17] offset:512
	global_load_dword v210, v144, s[16:17] offset:576
	global_load_dword v212, v144, s[16:17] offset:640
	global_load_dword v214, v144, s[16:17] offset:704
	s_mov_b32 s0, 0xbb7be14b
	s_mov_b32 s2, 0x3bcff2a2
	s_mov_b32 s28, 0xbc40d0ac
	s_mov_b32 s30, 0x3cb76c34
	s_mov_b32 s48, 0xbd17b858
	s_mov_b32 s50, 0x3d6537d1
	s_mov_b32 s52, 0xbdacab04
	s_mov_b32 s54, 0x3e342bfa
	v_mov_b32_e32 v198, s0
	v_and_b32_e32 v147, 64, v223
	v_add_u32_e32 v147, 64, v147
	v_xor_b32_e32 v146, 16, v223
	v_cmp_lt_i32_e32 vcc, v146, v147
	s_nop 1
	v_cndmask_b32_e32 v146, v223, v146, vcc
	v_lshlrev_b32_e32 v146, 2, v146
	v_xor_b32_e32 v148, 32, v223
	v_cmp_lt_i32_e32 vcc, v148, v147
	s_nop 1
	v_cndmask_b32_e32 v147, v223, v148, vcc
	v_lshlrev_b32_e32 v147, 2, v147
	s_add_i32 s94, s47, -16
	v_lshl_or_b32 v145, s94, 8, v176
	v_lshlrev_b32_e32 v148, 12, v142
	v_lshl_add_u32 v201, v145, 1, v148
	s_lshl_b32 s94, s94, 2
	s_or_b32 s94, s94, s43
	s_lshl_b32 s94, s94, 3
	v_lshlrev_b32_e32 v148, 8, v142
	v_add_u32_e32 v216, s94, v148
	v_add_u32_e32 v203, 0x10000, v201
	v_add_u32_e32 v217, 0x1000, v216
	v_add_u32_e32 v205, 0x20000, v201
	v_add_u32_e32 v218, 0x2000, v216
	v_add_u32_e32 v207, 0x30000, v201
	v_add_u32_e32 v219, 0x3000, v216
	v_add_u32_e32 v209, 0x80000, v201
	v_add_u32_e32 v220, 0x8000, v216
	v_add_u32_e32 v211, 0x90000, v201
	v_add_u32_e32 v221, 0x9000, v216
	v_add_u32_e32 v213, 0xa0000, v201
	v_add_u32_e32 v186, 0xa000, v216
	v_add_u32_e32 v215, 0xb0000, v201
	v_add_u32_e32 v187, 0xb000, v216
	s_waitcnt vmcnt(0)
	v_pk_mul_f32 v[128:129], v[128:129], v[200:201] op_sel_hi:[1,0]
	v_pk_mul_f32 v[130:131], v[130:131], v[200:201] op_sel_hi:[1,0]
	v_pk_mul_f32 v[120:121], v[120:121], v[200:201] op_sel_hi:[1,0]
	v_pk_mul_f32 v[122:123], v[122:123], v[200:201] op_sel_hi:[1,0]
	v_pk_mul_f32 v[124:125], v[124:125], v[200:201] op_sel_hi:[1,0]
	v_pk_mul_f32 v[126:127], v[126:127], v[200:201] op_sel_hi:[1,0]
	v_pk_mul_f32 v[116:117], v[116:117], v[200:201] op_sel_hi:[1,0]
	v_pk_mul_f32 v[118:119], v[118:119], v[200:201] op_sel_hi:[1,0]
	v_med3_f32 v158, v128, -4.0, 4.0
	v_med3_f32 v164, v130, -4.0, 4.0
	v_med3_f32 v170, v120, -4.0, 4.0
	v_med3_f32 v180, v122, -4.0, 4.0
	v_med3_f32 v159, v129, -4.0, 4.0
	v_med3_f32 v165, v131, -4.0, 4.0
	v_med3_f32 v171, v121, -4.0, 4.0
	v_med3_f32 v181, v123, -4.0, 4.0
	v_pk_mul_f32 v[160:161], v[158:159], v[158:159]
	v_pk_mul_f32 v[166:167], v[164:165], v[164:165]
	v_pk_mul_f32 v[172:173], v[170:171], v[170:171]
	v_pk_mul_f32 v[182:183], v[180:181], v[180:181]
	v_pk_fma_f32 v[160:161], v[160:161], s[72:73], -1.0 op_sel_hi:[1,0,0]
	v_pk_fma_f32 v[166:167], v[166:167], s[72:73], -1.0 op_sel_hi:[1,0,0]
	v_pk_fma_f32 v[172:173], v[172:173], s[72:73], -1.0 op_sel_hi:[1,0,0]
	v_pk_fma_f32 v[182:183], v[182:183], s[72:73], -1.0 op_sel_hi:[1,0,0]
	v_pk_fma_f32 v[162:163], v[160:161], s[74:75], v[198:199] op_sel_hi:[1,0,0]
	v_pk_fma_f32 v[168:169], v[166:167], s[74:75], v[198:199] op_sel_hi:[1,0,0]
	v_pk_fma_f32 v[178:179], v[172:173], s[74:75], v[198:199] op_sel_hi:[1,0,0]
	v_pk_fma_f32 v[184:185], v[182:183], s[74:75], v[198:199] op_sel_hi:[1,0,0]
	v_pk_fma_f32 v[162:163], v[160:161], v[162:163], s[2:3] op_sel_hi:[1,1,0]
	v_pk_fma_f32 v[168:169], v[166:167], v[168:169], s[2:3] op_sel_hi:[1,1,0]
	v_pk_fma_f32 v[178:179], v[172:173], v[178:179], s[2:3] op_sel_hi:[1,1,0]
	v_pk_fma_f32 v[184:185], v[182:183], v[184:185], s[2:3] op_sel_hi:[1,1,0]
	v_pk_fma_f32 v[162:163], v[160:161], v[162:163], s[28:29] op_sel_hi:[1,1,0]
	v_pk_fma_f32 v[168:169], v[166:167], v[168:169], s[28:29] op_sel_hi:[1,1,0]
	v_pk_fma_f32 v[178:179], v[172:173], v[178:179], s[28:29] op_sel_hi:[1,1,0]
	v_pk_fma_f32 v[184:185], v[182:183], v[184:185], s[28:29] op_sel_hi:[1,1,0]
	v_pk_fma_f32 v[162:163], v[160:161], v[162:163], s[30:31] op_sel_hi:[1,1,0]
	v_pk_fma_f32 v[168:169], v[166:167], v[168:169], s[30:31] op_sel_hi:[1,1,0]
	v_pk_fma_f32 v[178:179], v[172:173], v[178:179], s[30:31] op_sel_hi:[1,1,0]
	v_pk_fma_f32 v[184:185], v[182:183], v[184:185], s[30:31] op_sel_hi:[1,1,0]
	v_pk_fma_f32 v[162:163], v[160:161], v[162:163], s[48:49] op_sel_hi:[1,1,0]
	v_pk_fma_f32 v[168:169], v[166:167], v[168:169], s[48:49] op_sel_hi:[1,1,0]
	v_pk_fma_f32 v[178:179], v[172:173], v[178:179], s[48:49] op_sel_hi:[1,1,0]
	v_pk_fma_f32 v[184:185], v[182:183], v[184:185], s[48:49] op_sel_hi:[1,1,0]
	v_pk_fma_f32 v[162:163], v[160:161], v[162:163], s[50:51] op_sel_hi:[1,1,0]
	v_pk_fma_f32 v[168:169], v[166:167], v[168:169], s[50:51] op_sel_hi:[1,1,0]
	v_pk_fma_f32 v[178:179], v[172:173], v[178:179], s[50:51] op_sel_hi:[1,1,0]
	v_pk_fma_f32 v[184:185], v[182:183], v[184:185], s[50:51] op_sel_hi:[1,1,0]
	v_pk_fma_f32 v[162:163], v[160:161], v[162:163], s[52:53] op_sel_hi:[1,1,0]
	v_pk_fma_f32 v[168:169], v[166:167], v[168:169], s[52:53] op_sel_hi:[1,1,0]
	v_pk_fma_f32 v[178:179], v[172:173], v[178:179], s[52:53] op_sel_hi:[1,1,0]
	v_pk_fma_f32 v[184:185], v[182:183], v[184:185], s[52:53] op_sel_hi:[1,1,0]
	v_pk_fma_f32 v[160:161], v[160:161], v[162:163], s[54:55] op_sel_hi:[1,1,0]
	v_pk_fma_f32 v[166:167], v[166:167], v[168:169], s[54:55] op_sel_hi:[1,1,0]
	v_pk_fma_f32 v[172:173], v[172:173], v[178:179], s[54:55] op_sel_hi:[1,1,0]
	v_pk_fma_f32 v[182:183], v[182:183], v[184:185], s[54:55] op_sel_hi:[1,1,0]
	v_pk_fma_f32 v[158:159], v[158:159], v[160:161], 0.5 op_sel_hi:[1,1,0]
	v_pk_fma_f32 v[164:165], v[164:165], v[166:167], 0.5 op_sel_hi:[1,1,0]
	v_pk_fma_f32 v[170:171], v[170:171], v[172:173], 0.5 op_sel_hi:[1,1,0]
	v_pk_fma_f32 v[180:181], v[180:181], v[182:183], 0.5 op_sel_hi:[1,1,0]
	v_pk_mul_f32 v[128:129], v[128:129], v[158:159]
	v_pk_mul_f32 v[130:131], v[130:131], v[164:165]
	v_pk_mul_f32 v[120:121], v[120:121], v[170:171]
	v_pk_mul_f32 v[122:123], v[122:123], v[180:181]
	v_med3_f32 v158, v124, -4.0, 4.0
	v_med3_f32 v164, v126, -4.0, 4.0
	v_med3_f32 v170, v116, -4.0, 4.0
	v_med3_f32 v180, v118, -4.0, 4.0
	v_med3_f32 v159, v125, -4.0, 4.0
	v_med3_f32 v165, v127, -4.0, 4.0
	v_med3_f32 v171, v117, -4.0, 4.0
	v_med3_f32 v181, v119, -4.0, 4.0
	v_pk_mul_f32 v[160:161], v[158:159], v[158:159]
	v_pk_mul_f32 v[166:167], v[164:165], v[164:165]
	v_pk_mul_f32 v[172:173], v[170:171], v[170:171]
	v_pk_mul_f32 v[182:183], v[180:181], v[180:181]
	v_pk_fma_f32 v[160:161], v[160:161], s[72:73], -1.0 op_sel_hi:[1,0,0]
	v_pk_fma_f32 v[166:167], v[166:167], s[72:73], -1.0 op_sel_hi:[1,0,0]
	v_pk_fma_f32 v[172:173], v[172:173], s[72:73], -1.0 op_sel_hi:[1,0,0]
	v_pk_fma_f32 v[182:183], v[182:183], s[72:73], -1.0 op_sel_hi:[1,0,0]
	v_pk_fma_f32 v[162:163], v[160:161], s[74:75], v[198:199] op_sel_hi:[1,0,0]
	v_pk_fma_f32 v[168:169], v[166:167], s[74:75], v[198:199] op_sel_hi:[1,0,0]
	v_pk_fma_f32 v[178:179], v[172:173], s[74:75], v[198:199] op_sel_hi:[1,0,0]
	v_pk_fma_f32 v[184:185], v[182:183], s[74:75], v[198:199] op_sel_hi:[1,0,0]
	v_pk_fma_f32 v[162:163], v[160:161], v[162:163], s[2:3] op_sel_hi:[1,1,0]
	v_pk_fma_f32 v[168:169], v[166:167], v[168:169], s[2:3] op_sel_hi:[1,1,0]
	v_pk_fma_f32 v[178:179], v[172:173], v[178:179], s[2:3] op_sel_hi:[1,1,0]
	v_pk_fma_f32 v[184:185], v[182:183], v[184:185], s[2:3] op_sel_hi:[1,1,0]
	v_pk_fma_f32 v[162:163], v[160:161], v[162:163], s[28:29] op_sel_hi:[1,1,0]
	v_pk_fma_f32 v[168:169], v[166:167], v[168:169], s[28:29] op_sel_hi:[1,1,0]
	v_pk_fma_f32 v[178:179], v[172:173], v[178:179], s[28:29] op_sel_hi:[1,1,0]
	v_pk_fma_f32 v[184:185], v[182:183], v[184:185], s[28:29] op_sel_hi:[1,1,0]
	v_pk_fma_f32 v[162:163], v[160:161], v[162:163], s[30:31] op_sel_hi:[1,1,0]
	v_pk_fma_f32 v[168:169], v[166:167], v[168:169], s[30:31] op_sel_hi:[1,1,0]
	v_pk_fma_f32 v[178:179], v[172:173], v[178:179], s[30:31] op_sel_hi:[1,1,0]
	v_pk_fma_f32 v[184:185], v[182:183], v[184:185], s[30:31] op_sel_hi:[1,1,0]
	v_pk_fma_f32 v[162:163], v[160:161], v[162:163], s[48:49] op_sel_hi:[1,1,0]
	v_pk_fma_f32 v[168:169], v[166:167], v[168:169], s[48:49] op_sel_hi:[1,1,0]
	v_pk_fma_f32 v[178:179], v[172:173], v[178:179], s[48:49] op_sel_hi:[1,1,0]
	v_pk_fma_f32 v[184:185], v[182:183], v[184:185], s[48:49] op_sel_hi:[1,1,0]
	v_pk_fma_f32 v[162:163], v[160:161], v[162:163], s[50:51] op_sel_hi:[1,1,0]
	v_pk_fma_f32 v[168:169], v[166:167], v[168:169], s[50:51] op_sel_hi:[1,1,0]
	v_pk_fma_f32 v[178:179], v[172:173], v[178:179], s[50:51] op_sel_hi:[1,1,0]
	v_pk_fma_f32 v[184:185], v[182:183], v[184:185], s[50:51] op_sel_hi:[1,1,0]
	v_pk_fma_f32 v[162:163], v[160:161], v[162:163], s[52:53] op_sel_hi:[1,1,0]
	v_pk_fma_f32 v[168:169], v[166:167], v[168:169], s[52:53] op_sel_hi:[1,1,0]
	v_pk_fma_f32 v[178:179], v[172:173], v[178:179], s[52:53] op_sel_hi:[1,1,0]
	v_pk_fma_f32 v[184:185], v[182:183], v[184:185], s[52:53] op_sel_hi:[1,1,0]
	v_pk_fma_f32 v[160:161], v[160:161], v[162:163], s[54:55] op_sel_hi:[1,1,0]
	v_pk_fma_f32 v[166:167], v[166:167], v[168:169], s[54:55] op_sel_hi:[1,1,0]
	v_pk_fma_f32 v[172:173], v[172:173], v[178:179], s[54:55] op_sel_hi:[1,1,0]
	v_pk_fma_f32 v[182:183], v[182:183], v[184:185], s[54:55] op_sel_hi:[1,1,0]
	v_pk_fma_f32 v[158:159], v[158:159], v[160:161], 0.5 op_sel_hi:[1,1,0]
	v_pk_fma_f32 v[164:165], v[164:165], v[166:167], 0.5 op_sel_hi:[1,1,0]
	v_pk_fma_f32 v[170:171], v[170:171], v[172:173], 0.5 op_sel_hi:[1,1,0]
	v_pk_fma_f32 v[180:181], v[180:181], v[182:183], 0.5 op_sel_hi:[1,1,0]
	v_pk_mul_f32 v[124:125], v[124:125], v[158:159]
	v_pk_mul_f32 v[126:127], v[126:127], v[164:165]
	v_pk_mul_f32 v[116:117], v[116:117], v[170:171]
	v_pk_mul_f32 v[118:119], v[118:119], v[180:181]
	v_pk_add_f32 v[158:159], v[128:129], v[130:131]
	v_pk_add_f32 v[160:161], v[120:121], v[122:123]
	v_pk_add_f32 v[162:163], v[124:125], v[126:127]
	v_pk_add_f32 v[164:165], v[116:117], v[118:119]
	v_pk_mul_f32 v[166:167], v[128:129], v[128:129]
	v_pk_mul_f32 v[168:169], v[120:121], v[120:121]
	v_pk_mul_f32 v[170:171], v[124:125], v[124:125]
	v_pk_mul_f32 v[172:173], v[116:117], v[116:117]
	v_pk_fma_f32 v[166:167], v[130:131], v[130:131], v[166:167]
	v_pk_fma_f32 v[168:169], v[122:123], v[122:123], v[168:169]
	v_pk_fma_f32 v[170:171], v[126:127], v[126:127], v[170:171]
	v_pk_fma_f32 v[172:173], v[118:119], v[118:119], v[172:173]
	v_pk_add_f32 v[158:159], v[158:159], v[160:161]
	v_pk_add_f32 v[162:163], v[162:163], v[164:165]
	v_pk_add_f32 v[166:167], v[166:167], v[168:169]
	v_pk_add_f32 v[170:171], v[170:171], v[172:173]
	v_pk_add_f32 v[158:159], v[158:159], v[162:163]
	v_pk_add_f32 v[166:167], v[166:167], v[170:171]
	v_cvt_pk_bf16_f32 v128, v128, v129
	v_cvt_pk_bf16_f32 v129, v130, v131
	v_cvt_pk_bf16_f32 v130, v120, v121
	v_cvt_pk_bf16_f32 v131, v122, v123
	global_store_dwordx4 v201, v[128:131], s[12:13]
	v_cvt_pk_bf16_f32 v124, v124, v125
	v_cvt_pk_bf16_f32 v125, v126, v127
	v_cvt_pk_bf16_f32 v126, v116, v117
	v_cvt_pk_bf16_f32 v127, v118, v119
	global_store_dwordx4 v201, v[124:127], s[12:13] offset:256
	v_add_f32_e32 v120, v158, v159
	v_add_f32_e32 v121, v166, v167
	v_pk_mul_f32 v[112:113], v[112:113], v[202:203] op_sel_hi:[1,0]
	v_pk_mul_f32 v[114:115], v[114:115], v[202:203] op_sel_hi:[1,0]
	v_pk_mul_f32 v[104:105], v[104:105], v[202:203] op_sel_hi:[1,0]
	v_pk_mul_f32 v[106:107], v[106:107], v[202:203] op_sel_hi:[1,0]
	v_pk_mul_f32 v[108:109], v[108:109], v[202:203] op_sel_hi:[1,0]
	v_pk_mul_f32 v[110:111], v[110:111], v[202:203] op_sel_hi:[1,0]
	v_pk_mul_f32 v[100:101], v[100:101], v[202:203] op_sel_hi:[1,0]
	v_pk_mul_f32 v[102:103], v[102:103], v[202:203] op_sel_hi:[1,0]
	v_med3_f32 v158, v112, -4.0, 4.0
	v_med3_f32 v164, v114, -4.0, 4.0
	v_med3_f32 v170, v104, -4.0, 4.0
	v_med3_f32 v180, v106, -4.0, 4.0
	v_med3_f32 v159, v113, -4.0, 4.0
	v_med3_f32 v165, v115, -4.0, 4.0
	v_med3_f32 v171, v105, -4.0, 4.0
	v_med3_f32 v181, v107, -4.0, 4.0
	v_pk_mul_f32 v[160:161], v[158:159], v[158:159]
	v_pk_mul_f32 v[166:167], v[164:165], v[164:165]
	v_pk_mul_f32 v[172:173], v[170:171], v[170:171]
	v_pk_mul_f32 v[182:183], v[180:181], v[180:181]
	v_pk_fma_f32 v[160:161], v[160:161], s[72:73], -1.0 op_sel_hi:[1,0,0]
	v_pk_fma_f32 v[166:167], v[166:167], s[72:73], -1.0 op_sel_hi:[1,0,0]
	v_pk_fma_f32 v[172:173], v[172:173], s[72:73], -1.0 op_sel_hi:[1,0,0]
	v_pk_fma_f32 v[182:183], v[182:183], s[72:73], -1.0 op_sel_hi:[1,0,0]
	v_pk_fma_f32 v[162:163], v[160:161], s[74:75], v[198:199] op_sel_hi:[1,0,0]
	v_pk_fma_f32 v[168:169], v[166:167], s[74:75], v[198:199] op_sel_hi:[1,0,0]
	v_pk_fma_f32 v[178:179], v[172:173], s[74:75], v[198:199] op_sel_hi:[1,0,0]
	v_pk_fma_f32 v[184:185], v[182:183], s[74:75], v[198:199] op_sel_hi:[1,0,0]
	v_pk_fma_f32 v[162:163], v[160:161], v[162:163], s[2:3] op_sel_hi:[1,1,0]
	v_pk_fma_f32 v[168:169], v[166:167], v[168:169], s[2:3] op_sel_hi:[1,1,0]
	v_pk_fma_f32 v[178:179], v[172:173], v[178:179], s[2:3] op_sel_hi:[1,1,0]
	v_pk_fma_f32 v[184:185], v[182:183], v[184:185], s[2:3] op_sel_hi:[1,1,0]
	v_pk_fma_f32 v[162:163], v[160:161], v[162:163], s[28:29] op_sel_hi:[1,1,0]
	v_pk_fma_f32 v[168:169], v[166:167], v[168:169], s[28:29] op_sel_hi:[1,1,0]
	v_pk_fma_f32 v[178:179], v[172:173], v[178:179], s[28:29] op_sel_hi:[1,1,0]
	v_pk_fma_f32 v[184:185], v[182:183], v[184:185], s[28:29] op_sel_hi:[1,1,0]
	v_pk_fma_f32 v[162:163], v[160:161], v[162:163], s[30:31] op_sel_hi:[1,1,0]
	v_pk_fma_f32 v[168:169], v[166:167], v[168:169], s[30:31] op_sel_hi:[1,1,0]
	v_pk_fma_f32 v[178:179], v[172:173], v[178:179], s[30:31] op_sel_hi:[1,1,0]
	v_pk_fma_f32 v[184:185], v[182:183], v[184:185], s[30:31] op_sel_hi:[1,1,0]
	v_pk_fma_f32 v[162:163], v[160:161], v[162:163], s[48:49] op_sel_hi:[1,1,0]
	v_pk_fma_f32 v[168:169], v[166:167], v[168:169], s[48:49] op_sel_hi:[1,1,0]
	v_pk_fma_f32 v[178:179], v[172:173], v[178:179], s[48:49] op_sel_hi:[1,1,0]
	v_pk_fma_f32 v[184:185], v[182:183], v[184:185], s[48:49] op_sel_hi:[1,1,0]
	v_pk_fma_f32 v[162:163], v[160:161], v[162:163], s[50:51] op_sel_hi:[1,1,0]
	v_pk_fma_f32 v[168:169], v[166:167], v[168:169], s[50:51] op_sel_hi:[1,1,0]
	v_pk_fma_f32 v[178:179], v[172:173], v[178:179], s[50:51] op_sel_hi:[1,1,0]
	v_pk_fma_f32 v[184:185], v[182:183], v[184:185], s[50:51] op_sel_hi:[1,1,0]
	v_pk_fma_f32 v[162:163], v[160:161], v[162:163], s[52:53] op_sel_hi:[1,1,0]
	v_pk_fma_f32 v[168:169], v[166:167], v[168:169], s[52:53] op_sel_hi:[1,1,0]
	v_pk_fma_f32 v[178:179], v[172:173], v[178:179], s[52:53] op_sel_hi:[1,1,0]
	v_pk_fma_f32 v[184:185], v[182:183], v[184:185], s[52:53] op_sel_hi:[1,1,0]
	v_pk_fma_f32 v[160:161], v[160:161], v[162:163], s[54:55] op_sel_hi:[1,1,0]
	v_pk_fma_f32 v[166:167], v[166:167], v[168:169], s[54:55] op_sel_hi:[1,1,0]
	v_pk_fma_f32 v[172:173], v[172:173], v[178:179], s[54:55] op_sel_hi:[1,1,0]
	v_pk_fma_f32 v[182:183], v[182:183], v[184:185], s[54:55] op_sel_hi:[1,1,0]
	v_pk_fma_f32 v[158:159], v[158:159], v[160:161], 0.5 op_sel_hi:[1,1,0]
	v_pk_fma_f32 v[164:165], v[164:165], v[166:167], 0.5 op_sel_hi:[1,1,0]
	v_pk_fma_f32 v[170:171], v[170:171], v[172:173], 0.5 op_sel_hi:[1,1,0]
	v_pk_fma_f32 v[180:181], v[180:181], v[182:183], 0.5 op_sel_hi:[1,1,0]
	v_pk_mul_f32 v[112:113], v[112:113], v[158:159]
	v_pk_mul_f32 v[114:115], v[114:115], v[164:165]
	v_pk_mul_f32 v[104:105], v[104:105], v[170:171]
	v_pk_mul_f32 v[106:107], v[106:107], v[180:181]
	v_med3_f32 v158, v108, -4.0, 4.0
	v_med3_f32 v164, v110, -4.0, 4.0
	v_med3_f32 v170, v100, -4.0, 4.0
	v_med3_f32 v180, v102, -4.0, 4.0
	v_med3_f32 v159, v109, -4.0, 4.0
	v_med3_f32 v165, v111, -4.0, 4.0
	v_med3_f32 v171, v101, -4.0, 4.0
	v_med3_f32 v181, v103, -4.0, 4.0
	v_pk_mul_f32 v[160:161], v[158:159], v[158:159]
	v_pk_mul_f32 v[166:167], v[164:165], v[164:165]
	v_pk_mul_f32 v[172:173], v[170:171], v[170:171]
	v_pk_mul_f32 v[182:183], v[180:181], v[180:181]
	v_pk_fma_f32 v[160:161], v[160:161], s[72:73], -1.0 op_sel_hi:[1,0,0]
	v_pk_fma_f32 v[166:167], v[166:167], s[72:73], -1.0 op_sel_hi:[1,0,0]
	v_pk_fma_f32 v[172:173], v[172:173], s[72:73], -1.0 op_sel_hi:[1,0,0]
	v_pk_fma_f32 v[182:183], v[182:183], s[72:73], -1.0 op_sel_hi:[1,0,0]
	v_pk_fma_f32 v[162:163], v[160:161], s[74:75], v[198:199] op_sel_hi:[1,0,0]
	v_pk_fma_f32 v[168:169], v[166:167], s[74:75], v[198:199] op_sel_hi:[1,0,0]
	v_pk_fma_f32 v[178:179], v[172:173], s[74:75], v[198:199] op_sel_hi:[1,0,0]
	v_pk_fma_f32 v[184:185], v[182:183], s[74:75], v[198:199] op_sel_hi:[1,0,0]
	v_pk_fma_f32 v[162:163], v[160:161], v[162:163], s[2:3] op_sel_hi:[1,1,0]
	v_pk_fma_f32 v[168:169], v[166:167], v[168:169], s[2:3] op_sel_hi:[1,1,0]
	v_pk_fma_f32 v[178:179], v[172:173], v[178:179], s[2:3] op_sel_hi:[1,1,0]
	v_pk_fma_f32 v[184:185], v[182:183], v[184:185], s[2:3] op_sel_hi:[1,1,0]
	v_pk_fma_f32 v[162:163], v[160:161], v[162:163], s[28:29] op_sel_hi:[1,1,0]
	v_pk_fma_f32 v[168:169], v[166:167], v[168:169], s[28:29] op_sel_hi:[1,1,0]
	v_pk_fma_f32 v[178:179], v[172:173], v[178:179], s[28:29] op_sel_hi:[1,1,0]
	v_pk_fma_f32 v[184:185], v[182:183], v[184:185], s[28:29] op_sel_hi:[1,1,0]
	v_pk_fma_f32 v[162:163], v[160:161], v[162:163], s[30:31] op_sel_hi:[1,1,0]
	v_pk_fma_f32 v[168:169], v[166:167], v[168:169], s[30:31] op_sel_hi:[1,1,0]
	v_pk_fma_f32 v[178:179], v[172:173], v[178:179], s[30:31] op_sel_hi:[1,1,0]
	v_pk_fma_f32 v[184:185], v[182:183], v[184:185], s[30:31] op_sel_hi:[1,1,0]
	v_pk_fma_f32 v[162:163], v[160:161], v[162:163], s[48:49] op_sel_hi:[1,1,0]
	v_pk_fma_f32 v[168:169], v[166:167], v[168:169], s[48:49] op_sel_hi:[1,1,0]
	v_pk_fma_f32 v[178:179], v[172:173], v[178:179], s[48:49] op_sel_hi:[1,1,0]
	v_pk_fma_f32 v[184:185], v[182:183], v[184:185], s[48:49] op_sel_hi:[1,1,0]
	v_pk_fma_f32 v[162:163], v[160:161], v[162:163], s[50:51] op_sel_hi:[1,1,0]
	v_pk_fma_f32 v[168:169], v[166:167], v[168:169], s[50:51] op_sel_hi:[1,1,0]
	v_pk_fma_f32 v[178:179], v[172:173], v[178:179], s[50:51] op_sel_hi:[1,1,0]
	v_pk_fma_f32 v[184:185], v[182:183], v[184:185], s[50:51] op_sel_hi:[1,1,0]
	v_pk_fma_f32 v[162:163], v[160:161], v[162:163], s[52:53] op_sel_hi:[1,1,0]
	v_pk_fma_f32 v[168:169], v[166:167], v[168:169], s[52:53] op_sel_hi:[1,1,0]
	v_pk_fma_f32 v[178:179], v[172:173], v[178:179], s[52:53] op_sel_hi:[1,1,0]
	v_pk_fma_f32 v[184:185], v[182:183], v[184:185], s[52:53] op_sel_hi:[1,1,0]
	v_pk_fma_f32 v[160:161], v[160:161], v[162:163], s[54:55] op_sel_hi:[1,1,0]
	v_pk_fma_f32 v[166:167], v[166:167], v[168:169], s[54:55] op_sel_hi:[1,1,0]
	v_pk_fma_f32 v[172:173], v[172:173], v[178:179], s[54:55] op_sel_hi:[1,1,0]
	v_pk_fma_f32 v[182:183], v[182:183], v[184:185], s[54:55] op_sel_hi:[1,1,0]
	v_pk_fma_f32 v[158:159], v[158:159], v[160:161], 0.5 op_sel_hi:[1,1,0]
	v_pk_fma_f32 v[164:165], v[164:165], v[166:167], 0.5 op_sel_hi:[1,1,0]
	v_pk_fma_f32 v[170:171], v[170:171], v[172:173], 0.5 op_sel_hi:[1,1,0]
	v_pk_fma_f32 v[180:181], v[180:181], v[182:183], 0.5 op_sel_hi:[1,1,0]
	v_pk_mul_f32 v[108:109], v[108:109], v[158:159]
	v_pk_mul_f32 v[110:111], v[110:111], v[164:165]
	v_pk_mul_f32 v[100:101], v[100:101], v[170:171]
	v_pk_mul_f32 v[102:103], v[102:103], v[180:181]
	v_pk_add_f32 v[158:159], v[112:113], v[114:115]
	v_pk_add_f32 v[160:161], v[104:105], v[106:107]
	v_pk_add_f32 v[162:163], v[108:109], v[110:111]
	v_pk_add_f32 v[164:165], v[100:101], v[102:103]
	v_pk_mul_f32 v[166:167], v[112:113], v[112:113]
	v_pk_mul_f32 v[168:169], v[104:105], v[104:105]
	v_pk_mul_f32 v[170:171], v[108:109], v[108:109]
	v_pk_mul_f32 v[172:173], v[100:101], v[100:101]
	v_pk_fma_f32 v[166:167], v[114:115], v[114:115], v[166:167]
	v_pk_fma_f32 v[168:169], v[106:107], v[106:107], v[168:169]
	v_pk_fma_f32 v[170:171], v[110:111], v[110:111], v[170:171]
	v_pk_fma_f32 v[172:173], v[102:103], v[102:103], v[172:173]
	v_pk_add_f32 v[158:159], v[158:159], v[160:161]
	v_pk_add_f32 v[162:163], v[162:163], v[164:165]
	v_pk_add_f32 v[166:167], v[166:167], v[168:169]
	v_pk_add_f32 v[170:171], v[170:171], v[172:173]
	v_pk_add_f32 v[158:159], v[158:159], v[162:163]
	v_pk_add_f32 v[166:167], v[166:167], v[170:171]
	v_cvt_pk_bf16_f32 v112, v112, v113
	v_cvt_pk_bf16_f32 v113, v114, v115
	v_cvt_pk_bf16_f32 v114, v104, v105
	v_cvt_pk_bf16_f32 v115, v106, v107
	global_store_dwordx4 v203, v[112:115], s[12:13]
	v_cvt_pk_bf16_f32 v108, v108, v109
	v_cvt_pk_bf16_f32 v109, v110, v111
	v_cvt_pk_bf16_f32 v110, v100, v101
	v_cvt_pk_bf16_f32 v111, v102, v103
	global_store_dwordx4 v203, v[108:111], s[12:13] offset:256
	v_add_f32_e32 v104, v158, v159
	v_add_f32_e32 v105, v166, v167
	v_pk_mul_f32 v[96:97], v[96:97], v[204:205] op_sel_hi:[1,0]
	v_pk_mul_f32 v[98:99], v[98:99], v[204:205] op_sel_hi:[1,0]
	v_pk_mul_f32 v[88:89], v[88:89], v[204:205] op_sel_hi:[1,0]
	v_pk_mul_f32 v[90:91], v[90:91], v[204:205] op_sel_hi:[1,0]
	v_pk_mul_f32 v[92:93], v[92:93], v[204:205] op_sel_hi:[1,0]
	v_pk_mul_f32 v[94:95], v[94:95], v[204:205] op_sel_hi:[1,0]
	v_pk_mul_f32 v[84:85], v[84:85], v[204:205] op_sel_hi:[1,0]
	v_pk_mul_f32 v[86:87], v[86:87], v[204:205] op_sel_hi:[1,0]
	v_med3_f32 v158, v96, -4.0, 4.0
	v_med3_f32 v164, v98, -4.0, 4.0
	v_med3_f32 v170, v88, -4.0, 4.0
	v_med3_f32 v180, v90, -4.0, 4.0
	v_med3_f32 v159, v97, -4.0, 4.0
	v_med3_f32 v165, v99, -4.0, 4.0
	v_med3_f32 v171, v89, -4.0, 4.0
	v_med3_f32 v181, v91, -4.0, 4.0
	v_pk_mul_f32 v[160:161], v[158:159], v[158:159]
	v_pk_mul_f32 v[166:167], v[164:165], v[164:165]
	v_pk_mul_f32 v[172:173], v[170:171], v[170:171]
	v_pk_mul_f32 v[182:183], v[180:181], v[180:181]
	v_pk_fma_f32 v[160:161], v[160:161], s[72:73], -1.0 op_sel_hi:[1,0,0]
	v_pk_fma_f32 v[166:167], v[166:167], s[72:73], -1.0 op_sel_hi:[1,0,0]
	v_pk_fma_f32 v[172:173], v[172:173], s[72:73], -1.0 op_sel_hi:[1,0,0]
	v_pk_fma_f32 v[182:183], v[182:183], s[72:73], -1.0 op_sel_hi:[1,0,0]
	v_pk_fma_f32 v[162:163], v[160:161], s[74:75], v[198:199] op_sel_hi:[1,0,0]
	v_pk_fma_f32 v[168:169], v[166:167], s[74:75], v[198:199] op_sel_hi:[1,0,0]
	v_pk_fma_f32 v[178:179], v[172:173], s[74:75], v[198:199] op_sel_hi:[1,0,0]
	v_pk_fma_f32 v[184:185], v[182:183], s[74:75], v[198:199] op_sel_hi:[1,0,0]
	v_pk_fma_f32 v[162:163], v[160:161], v[162:163], s[2:3] op_sel_hi:[1,1,0]
	v_pk_fma_f32 v[168:169], v[166:167], v[168:169], s[2:3] op_sel_hi:[1,1,0]
	v_pk_fma_f32 v[178:179], v[172:173], v[178:179], s[2:3] op_sel_hi:[1,1,0]
	v_pk_fma_f32 v[184:185], v[182:183], v[184:185], s[2:3] op_sel_hi:[1,1,0]
	v_pk_fma_f32 v[162:163], v[160:161], v[162:163], s[28:29] op_sel_hi:[1,1,0]
	v_pk_fma_f32 v[168:169], v[166:167], v[168:169], s[28:29] op_sel_hi:[1,1,0]
	v_pk_fma_f32 v[178:179], v[172:173], v[178:179], s[28:29] op_sel_hi:[1,1,0]
	v_pk_fma_f32 v[184:185], v[182:183], v[184:185], s[28:29] op_sel_hi:[1,1,0]
	v_pk_fma_f32 v[162:163], v[160:161], v[162:163], s[30:31] op_sel_hi:[1,1,0]
	v_pk_fma_f32 v[168:169], v[166:167], v[168:169], s[30:31] op_sel_hi:[1,1,0]
	v_pk_fma_f32 v[178:179], v[172:173], v[178:179], s[30:31] op_sel_hi:[1,1,0]
	v_pk_fma_f32 v[184:185], v[182:183], v[184:185], s[30:31] op_sel_hi:[1,1,0]
	v_pk_fma_f32 v[162:163], v[160:161], v[162:163], s[48:49] op_sel_hi:[1,1,0]
	v_pk_fma_f32 v[168:169], v[166:167], v[168:169], s[48:49] op_sel_hi:[1,1,0]
	v_pk_fma_f32 v[178:179], v[172:173], v[178:179], s[48:49] op_sel_hi:[1,1,0]
	v_pk_fma_f32 v[184:185], v[182:183], v[184:185], s[48:49] op_sel_hi:[1,1,0]
	v_pk_fma_f32 v[162:163], v[160:161], v[162:163], s[50:51] op_sel_hi:[1,1,0]
	v_pk_fma_f32 v[168:169], v[166:167], v[168:169], s[50:51] op_sel_hi:[1,1,0]
	v_pk_fma_f32 v[178:179], v[172:173], v[178:179], s[50:51] op_sel_hi:[1,1,0]
	v_pk_fma_f32 v[184:185], v[182:183], v[184:185], s[50:51] op_sel_hi:[1,1,0]
	v_pk_fma_f32 v[162:163], v[160:161], v[162:163], s[52:53] op_sel_hi:[1,1,0]
	v_pk_fma_f32 v[168:169], v[166:167], v[168:169], s[52:53] op_sel_hi:[1,1,0]
	v_pk_fma_f32 v[178:179], v[172:173], v[178:179], s[52:53] op_sel_hi:[1,1,0]
	v_pk_fma_f32 v[184:185], v[182:183], v[184:185], s[52:53] op_sel_hi:[1,1,0]
	v_pk_fma_f32 v[160:161], v[160:161], v[162:163], s[54:55] op_sel_hi:[1,1,0]
	v_pk_fma_f32 v[166:167], v[166:167], v[168:169], s[54:55] op_sel_hi:[1,1,0]
	v_pk_fma_f32 v[172:173], v[172:173], v[178:179], s[54:55] op_sel_hi:[1,1,0]
	v_pk_fma_f32 v[182:183], v[182:183], v[184:185], s[54:55] op_sel_hi:[1,1,0]
	v_pk_fma_f32 v[158:159], v[158:159], v[160:161], 0.5 op_sel_hi:[1,1,0]
	v_pk_fma_f32 v[164:165], v[164:165], v[166:167], 0.5 op_sel_hi:[1,1,0]
	v_pk_fma_f32 v[170:171], v[170:171], v[172:173], 0.5 op_sel_hi:[1,1,0]
	v_pk_fma_f32 v[180:181], v[180:181], v[182:183], 0.5 op_sel_hi:[1,1,0]
	v_pk_mul_f32 v[96:97], v[96:97], v[158:159]
	v_pk_mul_f32 v[98:99], v[98:99], v[164:165]
	v_pk_mul_f32 v[88:89], v[88:89], v[170:171]
	v_pk_mul_f32 v[90:91], v[90:91], v[180:181]
	v_med3_f32 v158, v92, -4.0, 4.0
	v_med3_f32 v164, v94, -4.0, 4.0
	v_med3_f32 v170, v84, -4.0, 4.0
	v_med3_f32 v180, v86, -4.0, 4.0
	v_med3_f32 v159, v93, -4.0, 4.0
	v_med3_f32 v165, v95, -4.0, 4.0
	v_med3_f32 v171, v85, -4.0, 4.0
	v_med3_f32 v181, v87, -4.0, 4.0
	v_pk_mul_f32 v[160:161], v[158:159], v[158:159]
	v_pk_mul_f32 v[166:167], v[164:165], v[164:165]
	v_pk_mul_f32 v[172:173], v[170:171], v[170:171]
	v_pk_mul_f32 v[182:183], v[180:181], v[180:181]
	v_pk_fma_f32 v[160:161], v[160:161], s[72:73], -1.0 op_sel_hi:[1,0,0]
	v_pk_fma_f32 v[166:167], v[166:167], s[72:73], -1.0 op_sel_hi:[1,0,0]
	v_pk_fma_f32 v[172:173], v[172:173], s[72:73], -1.0 op_sel_hi:[1,0,0]
	v_pk_fma_f32 v[182:183], v[182:183], s[72:73], -1.0 op_sel_hi:[1,0,0]
	v_pk_fma_f32 v[162:163], v[160:161], s[74:75], v[198:199] op_sel_hi:[1,0,0]
	v_pk_fma_f32 v[168:169], v[166:167], s[74:75], v[198:199] op_sel_hi:[1,0,0]
	v_pk_fma_f32 v[178:179], v[172:173], s[74:75], v[198:199] op_sel_hi:[1,0,0]
	v_pk_fma_f32 v[184:185], v[182:183], s[74:75], v[198:199] op_sel_hi:[1,0,0]
	v_pk_fma_f32 v[162:163], v[160:161], v[162:163], s[2:3] op_sel_hi:[1,1,0]
	v_pk_fma_f32 v[168:169], v[166:167], v[168:169], s[2:3] op_sel_hi:[1,1,0]
	v_pk_fma_f32 v[178:179], v[172:173], v[178:179], s[2:3] op_sel_hi:[1,1,0]
	v_pk_fma_f32 v[184:185], v[182:183], v[184:185], s[2:3] op_sel_hi:[1,1,0]
	v_pk_fma_f32 v[162:163], v[160:161], v[162:163], s[28:29] op_sel_hi:[1,1,0]
	v_pk_fma_f32 v[168:169], v[166:167], v[168:169], s[28:29] op_sel_hi:[1,1,0]
	v_pk_fma_f32 v[178:179], v[172:173], v[178:179], s[28:29] op_sel_hi:[1,1,0]
	v_pk_fma_f32 v[184:185], v[182:183], v[184:185], s[28:29] op_sel_hi:[1,1,0]
	v_pk_fma_f32 v[162:163], v[160:161], v[162:163], s[30:31] op_sel_hi:[1,1,0]
	v_pk_fma_f32 v[168:169], v[166:167], v[168:169], s[30:31] op_sel_hi:[1,1,0]
	v_pk_fma_f32 v[178:179], v[172:173], v[178:179], s[30:31] op_sel_hi:[1,1,0]
	v_pk_fma_f32 v[184:185], v[182:183], v[184:185], s[30:31] op_sel_hi:[1,1,0]
	v_pk_fma_f32 v[162:163], v[160:161], v[162:163], s[48:49] op_sel_hi:[1,1,0]
	v_pk_fma_f32 v[168:169], v[166:167], v[168:169], s[48:49] op_sel_hi:[1,1,0]
	v_pk_fma_f32 v[178:179], v[172:173], v[178:179], s[48:49] op_sel_hi:[1,1,0]
	v_pk_fma_f32 v[184:185], v[182:183], v[184:185], s[48:49] op_sel_hi:[1,1,0]
	v_pk_fma_f32 v[162:163], v[160:161], v[162:163], s[50:51] op_sel_hi:[1,1,0]
	v_pk_fma_f32 v[168:169], v[166:167], v[168:169], s[50:51] op_sel_hi:[1,1,0]
	v_pk_fma_f32 v[178:179], v[172:173], v[178:179], s[50:51] op_sel_hi:[1,1,0]
	v_pk_fma_f32 v[184:185], v[182:183], v[184:185], s[50:51] op_sel_hi:[1,1,0]
	v_pk_fma_f32 v[162:163], v[160:161], v[162:163], s[52:53] op_sel_hi:[1,1,0]
	v_pk_fma_f32 v[168:169], v[166:167], v[168:169], s[52:53] op_sel_hi:[1,1,0]
	v_pk_fma_f32 v[178:179], v[172:173], v[178:179], s[52:53] op_sel_hi:[1,1,0]
	v_pk_fma_f32 v[184:185], v[182:183], v[184:185], s[52:53] op_sel_hi:[1,1,0]
	v_pk_fma_f32 v[160:161], v[160:161], v[162:163], s[54:55] op_sel_hi:[1,1,0]
	v_pk_fma_f32 v[166:167], v[166:167], v[168:169], s[54:55] op_sel_hi:[1,1,0]
	v_pk_fma_f32 v[172:173], v[172:173], v[178:179], s[54:55] op_sel_hi:[1,1,0]
	v_pk_fma_f32 v[182:183], v[182:183], v[184:185], s[54:55] op_sel_hi:[1,1,0]
	v_pk_fma_f32 v[158:159], v[158:159], v[160:161], 0.5 op_sel_hi:[1,1,0]
	v_pk_fma_f32 v[164:165], v[164:165], v[166:167], 0.5 op_sel_hi:[1,1,0]
	v_pk_fma_f32 v[170:171], v[170:171], v[172:173], 0.5 op_sel_hi:[1,1,0]
	v_pk_fma_f32 v[180:181], v[180:181], v[182:183], 0.5 op_sel_hi:[1,1,0]
	v_pk_mul_f32 v[92:93], v[92:93], v[158:159]
	v_pk_mul_f32 v[94:95], v[94:95], v[164:165]
	v_pk_mul_f32 v[84:85], v[84:85], v[170:171]
	v_pk_mul_f32 v[86:87], v[86:87], v[180:181]
	v_pk_add_f32 v[158:159], v[96:97], v[98:99]
	v_pk_add_f32 v[160:161], v[88:89], v[90:91]
	v_pk_add_f32 v[162:163], v[92:93], v[94:95]
	v_pk_add_f32 v[164:165], v[84:85], v[86:87]
	v_pk_mul_f32 v[166:167], v[96:97], v[96:97]
	v_pk_mul_f32 v[168:169], v[88:89], v[88:89]
	v_pk_mul_f32 v[170:171], v[92:93], v[92:93]
	v_pk_mul_f32 v[172:173], v[84:85], v[84:85]
	v_pk_fma_f32 v[166:167], v[98:99], v[98:99], v[166:167]
	v_pk_fma_f32 v[168:169], v[90:91], v[90:91], v[168:169]
	v_pk_fma_f32 v[170:171], v[94:95], v[94:95], v[170:171]
	v_pk_fma_f32 v[172:173], v[86:87], v[86:87], v[172:173]
	v_pk_add_f32 v[158:159], v[158:159], v[160:161]
	v_pk_add_f32 v[162:163], v[162:163], v[164:165]
	v_pk_add_f32 v[166:167], v[166:167], v[168:169]
	v_pk_add_f32 v[170:171], v[170:171], v[172:173]
	v_pk_add_f32 v[158:159], v[158:159], v[162:163]
	v_pk_add_f32 v[166:167], v[166:167], v[170:171]
	v_cvt_pk_bf16_f32 v96, v96, v97
	v_cvt_pk_bf16_f32 v97, v98, v99
	v_cvt_pk_bf16_f32 v98, v88, v89
	v_cvt_pk_bf16_f32 v99, v90, v91
	global_store_dwordx4 v205, v[96:99], s[12:13]
	v_cvt_pk_bf16_f32 v92, v92, v93
	v_cvt_pk_bf16_f32 v93, v94, v95
	v_cvt_pk_bf16_f32 v94, v84, v85
	v_cvt_pk_bf16_f32 v95, v86, v87
	global_store_dwordx4 v205, v[92:95], s[12:13] offset:256
	v_add_f32_e32 v88, v158, v159
	v_add_f32_e32 v89, v166, v167
	v_pk_mul_f32 v[80:81], v[80:81], v[206:207] op_sel_hi:[1,0]
	v_pk_mul_f32 v[82:83], v[82:83], v[206:207] op_sel_hi:[1,0]
	v_pk_mul_f32 v[72:73], v[72:73], v[206:207] op_sel_hi:[1,0]
	v_pk_mul_f32 v[74:75], v[74:75], v[206:207] op_sel_hi:[1,0]
	v_pk_mul_f32 v[76:77], v[76:77], v[206:207] op_sel_hi:[1,0]
	v_pk_mul_f32 v[78:79], v[78:79], v[206:207] op_sel_hi:[1,0]
	v_pk_mul_f32 v[68:69], v[68:69], v[206:207] op_sel_hi:[1,0]
	v_pk_mul_f32 v[70:71], v[70:71], v[206:207] op_sel_hi:[1,0]
	v_med3_f32 v158, v80, -4.0, 4.0
	v_med3_f32 v164, v82, -4.0, 4.0
	v_med3_f32 v170, v72, -4.0, 4.0
	v_med3_f32 v180, v74, -4.0, 4.0
	v_med3_f32 v159, v81, -4.0, 4.0
	v_med3_f32 v165, v83, -4.0, 4.0
	v_med3_f32 v171, v73, -4.0, 4.0
	v_med3_f32 v181, v75, -4.0, 4.0
	v_pk_mul_f32 v[160:161], v[158:159], v[158:159]
	v_pk_mul_f32 v[166:167], v[164:165], v[164:165]
	v_pk_mul_f32 v[172:173], v[170:171], v[170:171]
	v_pk_mul_f32 v[182:183], v[180:181], v[180:181]
	v_pk_fma_f32 v[160:161], v[160:161], s[72:73], -1.0 op_sel_hi:[1,0,0]
	v_pk_fma_f32 v[166:167], v[166:167], s[72:73], -1.0 op_sel_hi:[1,0,0]
	v_pk_fma_f32 v[172:173], v[172:173], s[72:73], -1.0 op_sel_hi:[1,0,0]
	v_pk_fma_f32 v[182:183], v[182:183], s[72:73], -1.0 op_sel_hi:[1,0,0]
	v_pk_fma_f32 v[162:163], v[160:161], s[74:75], v[198:199] op_sel_hi:[1,0,0]
	v_pk_fma_f32 v[168:169], v[166:167], s[74:75], v[198:199] op_sel_hi:[1,0,0]
	v_pk_fma_f32 v[178:179], v[172:173], s[74:75], v[198:199] op_sel_hi:[1,0,0]
	v_pk_fma_f32 v[184:185], v[182:183], s[74:75], v[198:199] op_sel_hi:[1,0,0]
	v_pk_fma_f32 v[162:163], v[160:161], v[162:163], s[2:3] op_sel_hi:[1,1,0]
	v_pk_fma_f32 v[168:169], v[166:167], v[168:169], s[2:3] op_sel_hi:[1,1,0]
	v_pk_fma_f32 v[178:179], v[172:173], v[178:179], s[2:3] op_sel_hi:[1,1,0]
	v_pk_fma_f32 v[184:185], v[182:183], v[184:185], s[2:3] op_sel_hi:[1,1,0]
	v_pk_fma_f32 v[162:163], v[160:161], v[162:163], s[28:29] op_sel_hi:[1,1,0]
	v_pk_fma_f32 v[168:169], v[166:167], v[168:169], s[28:29] op_sel_hi:[1,1,0]
	v_pk_fma_f32 v[178:179], v[172:173], v[178:179], s[28:29] op_sel_hi:[1,1,0]
	v_pk_fma_f32 v[184:185], v[182:183], v[184:185], s[28:29] op_sel_hi:[1,1,0]
	v_pk_fma_f32 v[162:163], v[160:161], v[162:163], s[30:31] op_sel_hi:[1,1,0]
	v_pk_fma_f32 v[168:169], v[166:167], v[168:169], s[30:31] op_sel_hi:[1,1,0]
	v_pk_fma_f32 v[178:179], v[172:173], v[178:179], s[30:31] op_sel_hi:[1,1,0]
	v_pk_fma_f32 v[184:185], v[182:183], v[184:185], s[30:31] op_sel_hi:[1,1,0]
	v_pk_fma_f32 v[162:163], v[160:161], v[162:163], s[48:49] op_sel_hi:[1,1,0]
	v_pk_fma_f32 v[168:169], v[166:167], v[168:169], s[48:49] op_sel_hi:[1,1,0]
	v_pk_fma_f32 v[178:179], v[172:173], v[178:179], s[48:49] op_sel_hi:[1,1,0]
	v_pk_fma_f32 v[184:185], v[182:183], v[184:185], s[48:49] op_sel_hi:[1,1,0]
	v_pk_fma_f32 v[162:163], v[160:161], v[162:163], s[50:51] op_sel_hi:[1,1,0]
	v_pk_fma_f32 v[168:169], v[166:167], v[168:169], s[50:51] op_sel_hi:[1,1,0]
	v_pk_fma_f32 v[178:179], v[172:173], v[178:179], s[50:51] op_sel_hi:[1,1,0]
	v_pk_fma_f32 v[184:185], v[182:183], v[184:185], s[50:51] op_sel_hi:[1,1,0]
	v_pk_fma_f32 v[162:163], v[160:161], v[162:163], s[52:53] op_sel_hi:[1,1,0]
	v_pk_fma_f32 v[168:169], v[166:167], v[168:169], s[52:53] op_sel_hi:[1,1,0]
	v_pk_fma_f32 v[178:179], v[172:173], v[178:179], s[52:53] op_sel_hi:[1,1,0]
	v_pk_fma_f32 v[184:185], v[182:183], v[184:185], s[52:53] op_sel_hi:[1,1,0]
	v_pk_fma_f32 v[160:161], v[160:161], v[162:163], s[54:55] op_sel_hi:[1,1,0]
	v_pk_fma_f32 v[166:167], v[166:167], v[168:169], s[54:55] op_sel_hi:[1,1,0]
	v_pk_fma_f32 v[172:173], v[172:173], v[178:179], s[54:55] op_sel_hi:[1,1,0]
	v_pk_fma_f32 v[182:183], v[182:183], v[184:185], s[54:55] op_sel_hi:[1,1,0]
	v_pk_fma_f32 v[158:159], v[158:159], v[160:161], 0.5 op_sel_hi:[1,1,0]
	v_pk_fma_f32 v[164:165], v[164:165], v[166:167], 0.5 op_sel_hi:[1,1,0]
	v_pk_fma_f32 v[170:171], v[170:171], v[172:173], 0.5 op_sel_hi:[1,1,0]
	v_pk_fma_f32 v[180:181], v[180:181], v[182:183], 0.5 op_sel_hi:[1,1,0]
	v_pk_mul_f32 v[80:81], v[80:81], v[158:159]
	v_pk_mul_f32 v[82:83], v[82:83], v[164:165]
	v_pk_mul_f32 v[72:73], v[72:73], v[170:171]
	v_pk_mul_f32 v[74:75], v[74:75], v[180:181]
	v_med3_f32 v158, v76, -4.0, 4.0
	v_med3_f32 v164, v78, -4.0, 4.0
	v_med3_f32 v170, v68, -4.0, 4.0
	v_med3_f32 v180, v70, -4.0, 4.0
	v_med3_f32 v159, v77, -4.0, 4.0
	v_med3_f32 v165, v79, -4.0, 4.0
	v_med3_f32 v171, v69, -4.0, 4.0
	v_med3_f32 v181, v71, -4.0, 4.0
	v_pk_mul_f32 v[160:161], v[158:159], v[158:159]
	v_pk_mul_f32 v[166:167], v[164:165], v[164:165]
	v_pk_mul_f32 v[172:173], v[170:171], v[170:171]
	v_pk_mul_f32 v[182:183], v[180:181], v[180:181]
	v_pk_fma_f32 v[160:161], v[160:161], s[72:73], -1.0 op_sel_hi:[1,0,0]
	v_pk_fma_f32 v[166:167], v[166:167], s[72:73], -1.0 op_sel_hi:[1,0,0]
	v_pk_fma_f32 v[172:173], v[172:173], s[72:73], -1.0 op_sel_hi:[1,0,0]
	v_pk_fma_f32 v[182:183], v[182:183], s[72:73], -1.0 op_sel_hi:[1,0,0]
	v_pk_fma_f32 v[162:163], v[160:161], s[74:75], v[198:199] op_sel_hi:[1,0,0]
	v_pk_fma_f32 v[168:169], v[166:167], s[74:75], v[198:199] op_sel_hi:[1,0,0]
	v_pk_fma_f32 v[178:179], v[172:173], s[74:75], v[198:199] op_sel_hi:[1,0,0]
	v_pk_fma_f32 v[184:185], v[182:183], s[74:75], v[198:199] op_sel_hi:[1,0,0]
	v_pk_fma_f32 v[162:163], v[160:161], v[162:163], s[2:3] op_sel_hi:[1,1,0]
	v_pk_fma_f32 v[168:169], v[166:167], v[168:169], s[2:3] op_sel_hi:[1,1,0]
	v_pk_fma_f32 v[178:179], v[172:173], v[178:179], s[2:3] op_sel_hi:[1,1,0]
	v_pk_fma_f32 v[184:185], v[182:183], v[184:185], s[2:3] op_sel_hi:[1,1,0]
	v_pk_fma_f32 v[162:163], v[160:161], v[162:163], s[28:29] op_sel_hi:[1,1,0]
	v_pk_fma_f32 v[168:169], v[166:167], v[168:169], s[28:29] op_sel_hi:[1,1,0]
	v_pk_fma_f32 v[178:179], v[172:173], v[178:179], s[28:29] op_sel_hi:[1,1,0]
	v_pk_fma_f32 v[184:185], v[182:183], v[184:185], s[28:29] op_sel_hi:[1,1,0]
	v_pk_fma_f32 v[162:163], v[160:161], v[162:163], s[30:31] op_sel_hi:[1,1,0]
	v_pk_fma_f32 v[168:169], v[166:167], v[168:169], s[30:31] op_sel_hi:[1,1,0]
	v_pk_fma_f32 v[178:179], v[172:173], v[178:179], s[30:31] op_sel_hi:[1,1,0]
	v_pk_fma_f32 v[184:185], v[182:183], v[184:185], s[30:31] op_sel_hi:[1,1,0]
	v_pk_fma_f32 v[162:163], v[160:161], v[162:163], s[48:49] op_sel_hi:[1,1,0]
	v_pk_fma_f32 v[168:169], v[166:167], v[168:169], s[48:49] op_sel_hi:[1,1,0]
	v_pk_fma_f32 v[178:179], v[172:173], v[178:179], s[48:49] op_sel_hi:[1,1,0]
	v_pk_fma_f32 v[184:185], v[182:183], v[184:185], s[48:49] op_sel_hi:[1,1,0]
	v_pk_fma_f32 v[162:163], v[160:161], v[162:163], s[50:51] op_sel_hi:[1,1,0]
	v_pk_fma_f32 v[168:169], v[166:167], v[168:169], s[50:51] op_sel_hi:[1,1,0]
	v_pk_fma_f32 v[178:179], v[172:173], v[178:179], s[50:51] op_sel_hi:[1,1,0]
	v_pk_fma_f32 v[184:185], v[182:183], v[184:185], s[50:51] op_sel_hi:[1,1,0]
	v_pk_fma_f32 v[162:163], v[160:161], v[162:163], s[52:53] op_sel_hi:[1,1,0]
	v_pk_fma_f32 v[168:169], v[166:167], v[168:169], s[52:53] op_sel_hi:[1,1,0]
	v_pk_fma_f32 v[178:179], v[172:173], v[178:179], s[52:53] op_sel_hi:[1,1,0]
	v_pk_fma_f32 v[184:185], v[182:183], v[184:185], s[52:53] op_sel_hi:[1,1,0]
	v_pk_fma_f32 v[160:161], v[160:161], v[162:163], s[54:55] op_sel_hi:[1,1,0]
	v_pk_fma_f32 v[166:167], v[166:167], v[168:169], s[54:55] op_sel_hi:[1,1,0]
	v_pk_fma_f32 v[172:173], v[172:173], v[178:179], s[54:55] op_sel_hi:[1,1,0]
	v_pk_fma_f32 v[182:183], v[182:183], v[184:185], s[54:55] op_sel_hi:[1,1,0]
	v_pk_fma_f32 v[158:159], v[158:159], v[160:161], 0.5 op_sel_hi:[1,1,0]
	v_pk_fma_f32 v[164:165], v[164:165], v[166:167], 0.5 op_sel_hi:[1,1,0]
	v_pk_fma_f32 v[170:171], v[170:171], v[172:173], 0.5 op_sel_hi:[1,1,0]
	v_pk_fma_f32 v[180:181], v[180:181], v[182:183], 0.5 op_sel_hi:[1,1,0]
	v_pk_mul_f32 v[76:77], v[76:77], v[158:159]
	v_pk_mul_f32 v[78:79], v[78:79], v[164:165]
	v_pk_mul_f32 v[68:69], v[68:69], v[170:171]
	v_pk_mul_f32 v[70:71], v[70:71], v[180:181]
	v_pk_add_f32 v[158:159], v[80:81], v[82:83]
	v_pk_add_f32 v[160:161], v[72:73], v[74:75]
	v_pk_add_f32 v[162:163], v[76:77], v[78:79]
	v_pk_add_f32 v[164:165], v[68:69], v[70:71]
	v_pk_mul_f32 v[166:167], v[80:81], v[80:81]
	v_pk_mul_f32 v[168:169], v[72:73], v[72:73]
	v_pk_mul_f32 v[170:171], v[76:77], v[76:77]
	v_pk_mul_f32 v[172:173], v[68:69], v[68:69]
	v_pk_fma_f32 v[166:167], v[82:83], v[82:83], v[166:167]
	v_pk_fma_f32 v[168:169], v[74:75], v[74:75], v[168:169]
	v_pk_fma_f32 v[170:171], v[78:79], v[78:79], v[170:171]
	v_pk_fma_f32 v[172:173], v[70:71], v[70:71], v[172:173]
	v_pk_add_f32 v[158:159], v[158:159], v[160:161]
	v_pk_add_f32 v[162:163], v[162:163], v[164:165]
	v_pk_add_f32 v[166:167], v[166:167], v[168:169]
	v_pk_add_f32 v[170:171], v[170:171], v[172:173]
	v_pk_add_f32 v[158:159], v[158:159], v[162:163]
	v_pk_add_f32 v[166:167], v[166:167], v[170:171]
	v_cvt_pk_bf16_f32 v80, v80, v81
	v_cvt_pk_bf16_f32 v81, v82, v83
	v_cvt_pk_bf16_f32 v82, v72, v73
	v_cvt_pk_bf16_f32 v83, v74, v75
	global_store_dwordx4 v207, v[80:83], s[12:13]
	v_cvt_pk_bf16_f32 v76, v76, v77
	v_cvt_pk_bf16_f32 v77, v78, v79
	v_cvt_pk_bf16_f32 v78, v68, v69
	v_cvt_pk_bf16_f32 v79, v70, v71
	global_store_dwordx4 v207, v[76:79], s[12:13] offset:256
	v_add_f32_e32 v72, v158, v159
	v_add_f32_e32 v73, v166, v167
	v_pk_mul_f32 v[64:65], v[64:65], v[208:209] op_sel_hi:[1,0]
	v_pk_mul_f32 v[66:67], v[66:67], v[208:209] op_sel_hi:[1,0]
	v_pk_mul_f32 v[56:57], v[56:57], v[208:209] op_sel_hi:[1,0]
	v_pk_mul_f32 v[58:59], v[58:59], v[208:209] op_sel_hi:[1,0]
	v_pk_mul_f32 v[60:61], v[60:61], v[208:209] op_sel_hi:[1,0]
	v_pk_mul_f32 v[62:63], v[62:63], v[208:209] op_sel_hi:[1,0]
	v_pk_mul_f32 v[52:53], v[52:53], v[208:209] op_sel_hi:[1,0]
	v_pk_mul_f32 v[54:55], v[54:55], v[208:209] op_sel_hi:[1,0]
	v_med3_f32 v158, v64, -4.0, 4.0
	v_med3_f32 v164, v66, -4.0, 4.0
	v_med3_f32 v170, v56, -4.0, 4.0
	v_med3_f32 v180, v58, -4.0, 4.0
	v_med3_f32 v159, v65, -4.0, 4.0
	v_med3_f32 v165, v67, -4.0, 4.0
	v_med3_f32 v171, v57, -4.0, 4.0
	v_med3_f32 v181, v59, -4.0, 4.0
	v_pk_mul_f32 v[160:161], v[158:159], v[158:159]
	v_pk_mul_f32 v[166:167], v[164:165], v[164:165]
	v_pk_mul_f32 v[172:173], v[170:171], v[170:171]
	v_pk_mul_f32 v[182:183], v[180:181], v[180:181]
	v_pk_fma_f32 v[160:161], v[160:161], s[72:73], -1.0 op_sel_hi:[1,0,0]
	v_pk_fma_f32 v[166:167], v[166:167], s[72:73], -1.0 op_sel_hi:[1,0,0]
	v_pk_fma_f32 v[172:173], v[172:173], s[72:73], -1.0 op_sel_hi:[1,0,0]
	v_pk_fma_f32 v[182:183], v[182:183], s[72:73], -1.0 op_sel_hi:[1,0,0]
	v_pk_fma_f32 v[162:163], v[160:161], s[74:75], v[198:199] op_sel_hi:[1,0,0]
	v_pk_fma_f32 v[168:169], v[166:167], s[74:75], v[198:199] op_sel_hi:[1,0,0]
	v_pk_fma_f32 v[178:179], v[172:173], s[74:75], v[198:199] op_sel_hi:[1,0,0]
	v_pk_fma_f32 v[184:185], v[182:183], s[74:75], v[198:199] op_sel_hi:[1,0,0]
	v_pk_fma_f32 v[162:163], v[160:161], v[162:163], s[2:3] op_sel_hi:[1,1,0]
	v_pk_fma_f32 v[168:169], v[166:167], v[168:169], s[2:3] op_sel_hi:[1,1,0]
	v_pk_fma_f32 v[178:179], v[172:173], v[178:179], s[2:3] op_sel_hi:[1,1,0]
	v_pk_fma_f32 v[184:185], v[182:183], v[184:185], s[2:3] op_sel_hi:[1,1,0]
	v_pk_fma_f32 v[162:163], v[160:161], v[162:163], s[28:29] op_sel_hi:[1,1,0]
	v_pk_fma_f32 v[168:169], v[166:167], v[168:169], s[28:29] op_sel_hi:[1,1,0]
	v_pk_fma_f32 v[178:179], v[172:173], v[178:179], s[28:29] op_sel_hi:[1,1,0]
	v_pk_fma_f32 v[184:185], v[182:183], v[184:185], s[28:29] op_sel_hi:[1,1,0]
	v_pk_fma_f32 v[162:163], v[160:161], v[162:163], s[30:31] op_sel_hi:[1,1,0]
	v_pk_fma_f32 v[168:169], v[166:167], v[168:169], s[30:31] op_sel_hi:[1,1,0]
	v_pk_fma_f32 v[178:179], v[172:173], v[178:179], s[30:31] op_sel_hi:[1,1,0]
	v_pk_fma_f32 v[184:185], v[182:183], v[184:185], s[30:31] op_sel_hi:[1,1,0]
	v_pk_fma_f32 v[162:163], v[160:161], v[162:163], s[48:49] op_sel_hi:[1,1,0]
	v_pk_fma_f32 v[168:169], v[166:167], v[168:169], s[48:49] op_sel_hi:[1,1,0]
	v_pk_fma_f32 v[178:179], v[172:173], v[178:179], s[48:49] op_sel_hi:[1,1,0]
	v_pk_fma_f32 v[184:185], v[182:183], v[184:185], s[48:49] op_sel_hi:[1,1,0]
	v_pk_fma_f32 v[162:163], v[160:161], v[162:163], s[50:51] op_sel_hi:[1,1,0]
	v_pk_fma_f32 v[168:169], v[166:167], v[168:169], s[50:51] op_sel_hi:[1,1,0]
	v_pk_fma_f32 v[178:179], v[172:173], v[178:179], s[50:51] op_sel_hi:[1,1,0]
	v_pk_fma_f32 v[184:185], v[182:183], v[184:185], s[50:51] op_sel_hi:[1,1,0]
	v_pk_fma_f32 v[162:163], v[160:161], v[162:163], s[52:53] op_sel_hi:[1,1,0]
	v_pk_fma_f32 v[168:169], v[166:167], v[168:169], s[52:53] op_sel_hi:[1,1,0]
	v_pk_fma_f32 v[178:179], v[172:173], v[178:179], s[52:53] op_sel_hi:[1,1,0]
	v_pk_fma_f32 v[184:185], v[182:183], v[184:185], s[52:53] op_sel_hi:[1,1,0]
	v_pk_fma_f32 v[160:161], v[160:161], v[162:163], s[54:55] op_sel_hi:[1,1,0]
	v_pk_fma_f32 v[166:167], v[166:167], v[168:169], s[54:55] op_sel_hi:[1,1,0]
	v_pk_fma_f32 v[172:173], v[172:173], v[178:179], s[54:55] op_sel_hi:[1,1,0]
	v_pk_fma_f32 v[182:183], v[182:183], v[184:185], s[54:55] op_sel_hi:[1,1,0]
	v_pk_fma_f32 v[158:159], v[158:159], v[160:161], 0.5 op_sel_hi:[1,1,0]
	v_pk_fma_f32 v[164:165], v[164:165], v[166:167], 0.5 op_sel_hi:[1,1,0]
	v_pk_fma_f32 v[170:171], v[170:171], v[172:173], 0.5 op_sel_hi:[1,1,0]
	v_pk_fma_f32 v[180:181], v[180:181], v[182:183], 0.5 op_sel_hi:[1,1,0]
	v_pk_mul_f32 v[64:65], v[64:65], v[158:159]
	v_pk_mul_f32 v[66:67], v[66:67], v[164:165]
	v_pk_mul_f32 v[56:57], v[56:57], v[170:171]
	v_pk_mul_f32 v[58:59], v[58:59], v[180:181]
	v_med3_f32 v158, v60, -4.0, 4.0
	v_med3_f32 v164, v62, -4.0, 4.0
	v_med3_f32 v170, v52, -4.0, 4.0
	v_med3_f32 v180, v54, -4.0, 4.0
	v_med3_f32 v159, v61, -4.0, 4.0
	v_med3_f32 v165, v63, -4.0, 4.0
	v_med3_f32 v171, v53, -4.0, 4.0
	v_med3_f32 v181, v55, -4.0, 4.0
	v_pk_mul_f32 v[160:161], v[158:159], v[158:159]
	v_pk_mul_f32 v[166:167], v[164:165], v[164:165]
	v_pk_mul_f32 v[172:173], v[170:171], v[170:171]
	v_pk_mul_f32 v[182:183], v[180:181], v[180:181]
	v_pk_fma_f32 v[160:161], v[160:161], s[72:73], -1.0 op_sel_hi:[1,0,0]
	v_pk_fma_f32 v[166:167], v[166:167], s[72:73], -1.0 op_sel_hi:[1,0,0]
	v_pk_fma_f32 v[172:173], v[172:173], s[72:73], -1.0 op_sel_hi:[1,0,0]
	v_pk_fma_f32 v[182:183], v[182:183], s[72:73], -1.0 op_sel_hi:[1,0,0]
	v_pk_fma_f32 v[162:163], v[160:161], s[74:75], v[198:199] op_sel_hi:[1,0,0]
	v_pk_fma_f32 v[168:169], v[166:167], s[74:75], v[198:199] op_sel_hi:[1,0,0]
	v_pk_fma_f32 v[178:179], v[172:173], s[74:75], v[198:199] op_sel_hi:[1,0,0]
	v_pk_fma_f32 v[184:185], v[182:183], s[74:75], v[198:199] op_sel_hi:[1,0,0]
	v_pk_fma_f32 v[162:163], v[160:161], v[162:163], s[2:3] op_sel_hi:[1,1,0]
	v_pk_fma_f32 v[168:169], v[166:167], v[168:169], s[2:3] op_sel_hi:[1,1,0]
	v_pk_fma_f32 v[178:179], v[172:173], v[178:179], s[2:3] op_sel_hi:[1,1,0]
	v_pk_fma_f32 v[184:185], v[182:183], v[184:185], s[2:3] op_sel_hi:[1,1,0]
	v_pk_fma_f32 v[162:163], v[160:161], v[162:163], s[28:29] op_sel_hi:[1,1,0]
	v_pk_fma_f32 v[168:169], v[166:167], v[168:169], s[28:29] op_sel_hi:[1,1,0]
	v_pk_fma_f32 v[178:179], v[172:173], v[178:179], s[28:29] op_sel_hi:[1,1,0]
	v_pk_fma_f32 v[184:185], v[182:183], v[184:185], s[28:29] op_sel_hi:[1,1,0]
	v_pk_fma_f32 v[162:163], v[160:161], v[162:163], s[30:31] op_sel_hi:[1,1,0]
	v_pk_fma_f32 v[168:169], v[166:167], v[168:169], s[30:31] op_sel_hi:[1,1,0]
	v_pk_fma_f32 v[178:179], v[172:173], v[178:179], s[30:31] op_sel_hi:[1,1,0]
	v_pk_fma_f32 v[184:185], v[182:183], v[184:185], s[30:31] op_sel_hi:[1,1,0]
	v_pk_fma_f32 v[162:163], v[160:161], v[162:163], s[48:49] op_sel_hi:[1,1,0]
	v_pk_fma_f32 v[168:169], v[166:167], v[168:169], s[48:49] op_sel_hi:[1,1,0]
	v_pk_fma_f32 v[178:179], v[172:173], v[178:179], s[48:49] op_sel_hi:[1,1,0]
	v_pk_fma_f32 v[184:185], v[182:183], v[184:185], s[48:49] op_sel_hi:[1,1,0]
	v_pk_fma_f32 v[162:163], v[160:161], v[162:163], s[50:51] op_sel_hi:[1,1,0]
	v_pk_fma_f32 v[168:169], v[166:167], v[168:169], s[50:51] op_sel_hi:[1,1,0]
	v_pk_fma_f32 v[178:179], v[172:173], v[178:179], s[50:51] op_sel_hi:[1,1,0]
	v_pk_fma_f32 v[184:185], v[182:183], v[184:185], s[50:51] op_sel_hi:[1,1,0]
	v_pk_fma_f32 v[162:163], v[160:161], v[162:163], s[52:53] op_sel_hi:[1,1,0]
	v_pk_fma_f32 v[168:169], v[166:167], v[168:169], s[52:53] op_sel_hi:[1,1,0]
	v_pk_fma_f32 v[178:179], v[172:173], v[178:179], s[52:53] op_sel_hi:[1,1,0]
	v_pk_fma_f32 v[184:185], v[182:183], v[184:185], s[52:53] op_sel_hi:[1,1,0]
	v_pk_fma_f32 v[160:161], v[160:161], v[162:163], s[54:55] op_sel_hi:[1,1,0]
	v_pk_fma_f32 v[166:167], v[166:167], v[168:169], s[54:55] op_sel_hi:[1,1,0]
	v_pk_fma_f32 v[172:173], v[172:173], v[178:179], s[54:55] op_sel_hi:[1,1,0]
	v_pk_fma_f32 v[182:183], v[182:183], v[184:185], s[54:55] op_sel_hi:[1,1,0]
	v_pk_fma_f32 v[158:159], v[158:159], v[160:161], 0.5 op_sel_hi:[1,1,0]
	v_pk_fma_f32 v[164:165], v[164:165], v[166:167], 0.5 op_sel_hi:[1,1,0]
	v_pk_fma_f32 v[170:171], v[170:171], v[172:173], 0.5 op_sel_hi:[1,1,0]
	v_pk_fma_f32 v[180:181], v[180:181], v[182:183], 0.5 op_sel_hi:[1,1,0]
	v_pk_mul_f32 v[60:61], v[60:61], v[158:159]
	v_pk_mul_f32 v[62:63], v[62:63], v[164:165]
	v_pk_mul_f32 v[52:53], v[52:53], v[170:171]
	v_pk_mul_f32 v[54:55], v[54:55], v[180:181]
	v_pk_add_f32 v[158:159], v[64:65], v[66:67]
	v_pk_add_f32 v[160:161], v[56:57], v[58:59]
	v_pk_add_f32 v[162:163], v[60:61], v[62:63]
	v_pk_add_f32 v[164:165], v[52:53], v[54:55]
	v_pk_mul_f32 v[166:167], v[64:65], v[64:65]
	v_pk_mul_f32 v[168:169], v[56:57], v[56:57]
	v_pk_mul_f32 v[170:171], v[60:61], v[60:61]
	v_pk_mul_f32 v[172:173], v[52:53], v[52:53]
	v_pk_fma_f32 v[166:167], v[66:67], v[66:67], v[166:167]
	v_pk_fma_f32 v[168:169], v[58:59], v[58:59], v[168:169]
	v_pk_fma_f32 v[170:171], v[62:63], v[62:63], v[170:171]
	v_pk_fma_f32 v[172:173], v[54:55], v[54:55], v[172:173]
	v_pk_add_f32 v[158:159], v[158:159], v[160:161]
	v_pk_add_f32 v[162:163], v[162:163], v[164:165]
	v_pk_add_f32 v[166:167], v[166:167], v[168:169]
	v_pk_add_f32 v[170:171], v[170:171], v[172:173]
	v_pk_add_f32 v[158:159], v[158:159], v[162:163]
	v_pk_add_f32 v[166:167], v[166:167], v[170:171]
	v_cvt_pk_bf16_f32 v64, v64, v65
	v_cvt_pk_bf16_f32 v65, v66, v67
	v_cvt_pk_bf16_f32 v66, v56, v57
	v_cvt_pk_bf16_f32 v67, v58, v59
	global_store_dwordx4 v209, v[64:67], s[12:13]
	v_cvt_pk_bf16_f32 v60, v60, v61
	v_cvt_pk_bf16_f32 v61, v62, v63
	v_cvt_pk_bf16_f32 v62, v52, v53
	v_cvt_pk_bf16_f32 v63, v54, v55
	global_store_dwordx4 v209, v[60:63], s[12:13] offset:256
	v_add_f32_e32 v56, v158, v159
	v_add_f32_e32 v57, v166, v167
	v_pk_mul_f32 v[48:49], v[48:49], v[210:211] op_sel_hi:[1,0]
	v_pk_mul_f32 v[50:51], v[50:51], v[210:211] op_sel_hi:[1,0]
	v_pk_mul_f32 v[40:41], v[40:41], v[210:211] op_sel_hi:[1,0]
	v_pk_mul_f32 v[42:43], v[42:43], v[210:211] op_sel_hi:[1,0]
	v_pk_mul_f32 v[44:45], v[44:45], v[210:211] op_sel_hi:[1,0]
	v_pk_mul_f32 v[46:47], v[46:47], v[210:211] op_sel_hi:[1,0]
	v_pk_mul_f32 v[36:37], v[36:37], v[210:211] op_sel_hi:[1,0]
	v_pk_mul_f32 v[38:39], v[38:39], v[210:211] op_sel_hi:[1,0]
	v_med3_f32 v158, v48, -4.0, 4.0
	v_med3_f32 v164, v50, -4.0, 4.0
	v_med3_f32 v170, v40, -4.0, 4.0
	v_med3_f32 v180, v42, -4.0, 4.0
	v_med3_f32 v159, v49, -4.0, 4.0
	v_med3_f32 v165, v51, -4.0, 4.0
	v_med3_f32 v171, v41, -4.0, 4.0
	v_med3_f32 v181, v43, -4.0, 4.0
	v_pk_mul_f32 v[160:161], v[158:159], v[158:159]
	v_pk_mul_f32 v[166:167], v[164:165], v[164:165]
	v_pk_mul_f32 v[172:173], v[170:171], v[170:171]
	v_pk_mul_f32 v[182:183], v[180:181], v[180:181]
	v_pk_fma_f32 v[160:161], v[160:161], s[72:73], -1.0 op_sel_hi:[1,0,0]
	v_pk_fma_f32 v[166:167], v[166:167], s[72:73], -1.0 op_sel_hi:[1,0,0]
	v_pk_fma_f32 v[172:173], v[172:173], s[72:73], -1.0 op_sel_hi:[1,0,0]
	v_pk_fma_f32 v[182:183], v[182:183], s[72:73], -1.0 op_sel_hi:[1,0,0]
	v_pk_fma_f32 v[162:163], v[160:161], s[74:75], v[198:199] op_sel_hi:[1,0,0]
	v_pk_fma_f32 v[168:169], v[166:167], s[74:75], v[198:199] op_sel_hi:[1,0,0]
	v_pk_fma_f32 v[178:179], v[172:173], s[74:75], v[198:199] op_sel_hi:[1,0,0]
	v_pk_fma_f32 v[184:185], v[182:183], s[74:75], v[198:199] op_sel_hi:[1,0,0]
	v_pk_fma_f32 v[162:163], v[160:161], v[162:163], s[2:3] op_sel_hi:[1,1,0]
	v_pk_fma_f32 v[168:169], v[166:167], v[168:169], s[2:3] op_sel_hi:[1,1,0]
	v_pk_fma_f32 v[178:179], v[172:173], v[178:179], s[2:3] op_sel_hi:[1,1,0]
	v_pk_fma_f32 v[184:185], v[182:183], v[184:185], s[2:3] op_sel_hi:[1,1,0]
	v_pk_fma_f32 v[162:163], v[160:161], v[162:163], s[28:29] op_sel_hi:[1,1,0]
	v_pk_fma_f32 v[168:169], v[166:167], v[168:169], s[28:29] op_sel_hi:[1,1,0]
	v_pk_fma_f32 v[178:179], v[172:173], v[178:179], s[28:29] op_sel_hi:[1,1,0]
	v_pk_fma_f32 v[184:185], v[182:183], v[184:185], s[28:29] op_sel_hi:[1,1,0]
	v_pk_fma_f32 v[162:163], v[160:161], v[162:163], s[30:31] op_sel_hi:[1,1,0]
	v_pk_fma_f32 v[168:169], v[166:167], v[168:169], s[30:31] op_sel_hi:[1,1,0]
	v_pk_fma_f32 v[178:179], v[172:173], v[178:179], s[30:31] op_sel_hi:[1,1,0]
	v_pk_fma_f32 v[184:185], v[182:183], v[184:185], s[30:31] op_sel_hi:[1,1,0]
	v_pk_fma_f32 v[162:163], v[160:161], v[162:163], s[48:49] op_sel_hi:[1,1,0]
	v_pk_fma_f32 v[168:169], v[166:167], v[168:169], s[48:49] op_sel_hi:[1,1,0]
	v_pk_fma_f32 v[178:179], v[172:173], v[178:179], s[48:49] op_sel_hi:[1,1,0]
	v_pk_fma_f32 v[184:185], v[182:183], v[184:185], s[48:49] op_sel_hi:[1,1,0]
	v_pk_fma_f32 v[162:163], v[160:161], v[162:163], s[50:51] op_sel_hi:[1,1,0]
	v_pk_fma_f32 v[168:169], v[166:167], v[168:169], s[50:51] op_sel_hi:[1,1,0]
	v_pk_fma_f32 v[178:179], v[172:173], v[178:179], s[50:51] op_sel_hi:[1,1,0]
	v_pk_fma_f32 v[184:185], v[182:183], v[184:185], s[50:51] op_sel_hi:[1,1,0]
	v_pk_fma_f32 v[162:163], v[160:161], v[162:163], s[52:53] op_sel_hi:[1,1,0]
	v_pk_fma_f32 v[168:169], v[166:167], v[168:169], s[52:53] op_sel_hi:[1,1,0]
	v_pk_fma_f32 v[178:179], v[172:173], v[178:179], s[52:53] op_sel_hi:[1,1,0]
	v_pk_fma_f32 v[184:185], v[182:183], v[184:185], s[52:53] op_sel_hi:[1,1,0]
	v_pk_fma_f32 v[160:161], v[160:161], v[162:163], s[54:55] op_sel_hi:[1,1,0]
	v_pk_fma_f32 v[166:167], v[166:167], v[168:169], s[54:55] op_sel_hi:[1,1,0]
	v_pk_fma_f32 v[172:173], v[172:173], v[178:179], s[54:55] op_sel_hi:[1,1,0]
	v_pk_fma_f32 v[182:183], v[182:183], v[184:185], s[54:55] op_sel_hi:[1,1,0]
	v_pk_fma_f32 v[158:159], v[158:159], v[160:161], 0.5 op_sel_hi:[1,1,0]
	v_pk_fma_f32 v[164:165], v[164:165], v[166:167], 0.5 op_sel_hi:[1,1,0]
	v_pk_fma_f32 v[170:171], v[170:171], v[172:173], 0.5 op_sel_hi:[1,1,0]
	v_pk_fma_f32 v[180:181], v[180:181], v[182:183], 0.5 op_sel_hi:[1,1,0]
	v_pk_mul_f32 v[48:49], v[48:49], v[158:159]
	v_pk_mul_f32 v[50:51], v[50:51], v[164:165]
	v_pk_mul_f32 v[40:41], v[40:41], v[170:171]
	v_pk_mul_f32 v[42:43], v[42:43], v[180:181]
	v_med3_f32 v158, v44, -4.0, 4.0
	v_med3_f32 v164, v46, -4.0, 4.0
	v_med3_f32 v170, v36, -4.0, 4.0
	v_med3_f32 v180, v38, -4.0, 4.0
	v_med3_f32 v159, v45, -4.0, 4.0
	v_med3_f32 v165, v47, -4.0, 4.0
	v_med3_f32 v171, v37, -4.0, 4.0
	v_med3_f32 v181, v39, -4.0, 4.0
	v_pk_mul_f32 v[160:161], v[158:159], v[158:159]
	v_pk_mul_f32 v[166:167], v[164:165], v[164:165]
	v_pk_mul_f32 v[172:173], v[170:171], v[170:171]
	v_pk_mul_f32 v[182:183], v[180:181], v[180:181]
	v_pk_fma_f32 v[160:161], v[160:161], s[72:73], -1.0 op_sel_hi:[1,0,0]
	v_pk_fma_f32 v[166:167], v[166:167], s[72:73], -1.0 op_sel_hi:[1,0,0]
	v_pk_fma_f32 v[172:173], v[172:173], s[72:73], -1.0 op_sel_hi:[1,0,0]
	v_pk_fma_f32 v[182:183], v[182:183], s[72:73], -1.0 op_sel_hi:[1,0,0]
	v_pk_fma_f32 v[162:163], v[160:161], s[74:75], v[198:199] op_sel_hi:[1,0,0]
	v_pk_fma_f32 v[168:169], v[166:167], s[74:75], v[198:199] op_sel_hi:[1,0,0]
	v_pk_fma_f32 v[178:179], v[172:173], s[74:75], v[198:199] op_sel_hi:[1,0,0]
	v_pk_fma_f32 v[184:185], v[182:183], s[74:75], v[198:199] op_sel_hi:[1,0,0]
	v_pk_fma_f32 v[162:163], v[160:161], v[162:163], s[2:3] op_sel_hi:[1,1,0]
	v_pk_fma_f32 v[168:169], v[166:167], v[168:169], s[2:3] op_sel_hi:[1,1,0]
	v_pk_fma_f32 v[178:179], v[172:173], v[178:179], s[2:3] op_sel_hi:[1,1,0]
	v_pk_fma_f32 v[184:185], v[182:183], v[184:185], s[2:3] op_sel_hi:[1,1,0]
	v_pk_fma_f32 v[162:163], v[160:161], v[162:163], s[28:29] op_sel_hi:[1,1,0]
	v_pk_fma_f32 v[168:169], v[166:167], v[168:169], s[28:29] op_sel_hi:[1,1,0]
	v_pk_fma_f32 v[178:179], v[172:173], v[178:179], s[28:29] op_sel_hi:[1,1,0]
	v_pk_fma_f32 v[184:185], v[182:183], v[184:185], s[28:29] op_sel_hi:[1,1,0]
	v_pk_fma_f32 v[162:163], v[160:161], v[162:163], s[30:31] op_sel_hi:[1,1,0]
	v_pk_fma_f32 v[168:169], v[166:167], v[168:169], s[30:31] op_sel_hi:[1,1,0]
	v_pk_fma_f32 v[178:179], v[172:173], v[178:179], s[30:31] op_sel_hi:[1,1,0]
	v_pk_fma_f32 v[184:185], v[182:183], v[184:185], s[30:31] op_sel_hi:[1,1,0]
	v_pk_fma_f32 v[162:163], v[160:161], v[162:163], s[48:49] op_sel_hi:[1,1,0]
	v_pk_fma_f32 v[168:169], v[166:167], v[168:169], s[48:49] op_sel_hi:[1,1,0]
	v_pk_fma_f32 v[178:179], v[172:173], v[178:179], s[48:49] op_sel_hi:[1,1,0]
	v_pk_fma_f32 v[184:185], v[182:183], v[184:185], s[48:49] op_sel_hi:[1,1,0]
	v_pk_fma_f32 v[162:163], v[160:161], v[162:163], s[50:51] op_sel_hi:[1,1,0]
	v_pk_fma_f32 v[168:169], v[166:167], v[168:169], s[50:51] op_sel_hi:[1,1,0]
	v_pk_fma_f32 v[178:179], v[172:173], v[178:179], s[50:51] op_sel_hi:[1,1,0]
	v_pk_fma_f32 v[184:185], v[182:183], v[184:185], s[50:51] op_sel_hi:[1,1,0]
	v_pk_fma_f32 v[162:163], v[160:161], v[162:163], s[52:53] op_sel_hi:[1,1,0]
	v_pk_fma_f32 v[168:169], v[166:167], v[168:169], s[52:53] op_sel_hi:[1,1,0]
	v_pk_fma_f32 v[178:179], v[172:173], v[178:179], s[52:53] op_sel_hi:[1,1,0]
	v_pk_fma_f32 v[184:185], v[182:183], v[184:185], s[52:53] op_sel_hi:[1,1,0]
	v_pk_fma_f32 v[160:161], v[160:161], v[162:163], s[54:55] op_sel_hi:[1,1,0]
	v_pk_fma_f32 v[166:167], v[166:167], v[168:169], s[54:55] op_sel_hi:[1,1,0]
	v_pk_fma_f32 v[172:173], v[172:173], v[178:179], s[54:55] op_sel_hi:[1,1,0]
	v_pk_fma_f32 v[182:183], v[182:183], v[184:185], s[54:55] op_sel_hi:[1,1,0]
	v_pk_fma_f32 v[158:159], v[158:159], v[160:161], 0.5 op_sel_hi:[1,1,0]
	v_pk_fma_f32 v[164:165], v[164:165], v[166:167], 0.5 op_sel_hi:[1,1,0]
	v_pk_fma_f32 v[170:171], v[170:171], v[172:173], 0.5 op_sel_hi:[1,1,0]
	v_pk_fma_f32 v[180:181], v[180:181], v[182:183], 0.5 op_sel_hi:[1,1,0]
	v_pk_mul_f32 v[44:45], v[44:45], v[158:159]
	v_pk_mul_f32 v[46:47], v[46:47], v[164:165]
	v_pk_mul_f32 v[36:37], v[36:37], v[170:171]
	v_pk_mul_f32 v[38:39], v[38:39], v[180:181]
	v_pk_add_f32 v[158:159], v[48:49], v[50:51]
	v_pk_add_f32 v[160:161], v[40:41], v[42:43]
	v_pk_add_f32 v[162:163], v[44:45], v[46:47]
	v_pk_add_f32 v[164:165], v[36:37], v[38:39]
	v_pk_mul_f32 v[166:167], v[48:49], v[48:49]
	v_pk_mul_f32 v[168:169], v[40:41], v[40:41]
	v_pk_mul_f32 v[170:171], v[44:45], v[44:45]
	v_pk_mul_f32 v[172:173], v[36:37], v[36:37]
	v_pk_fma_f32 v[166:167], v[50:51], v[50:51], v[166:167]
	v_pk_fma_f32 v[168:169], v[42:43], v[42:43], v[168:169]
	v_pk_fma_f32 v[170:171], v[46:47], v[46:47], v[170:171]
	v_pk_fma_f32 v[172:173], v[38:39], v[38:39], v[172:173]
	v_pk_add_f32 v[158:159], v[158:159], v[160:161]
	v_pk_add_f32 v[162:163], v[162:163], v[164:165]
	v_pk_add_f32 v[166:167], v[166:167], v[168:169]
	v_pk_add_f32 v[170:171], v[170:171], v[172:173]
	v_pk_add_f32 v[158:159], v[158:159], v[162:163]
	v_pk_add_f32 v[166:167], v[166:167], v[170:171]
	v_cvt_pk_bf16_f32 v48, v48, v49
	v_cvt_pk_bf16_f32 v49, v50, v51
	v_cvt_pk_bf16_f32 v50, v40, v41
	v_cvt_pk_bf16_f32 v51, v42, v43
	global_store_dwordx4 v211, v[48:51], s[12:13]
	v_cvt_pk_bf16_f32 v44, v44, v45
	v_cvt_pk_bf16_f32 v45, v46, v47
	v_cvt_pk_bf16_f32 v46, v36, v37
	v_cvt_pk_bf16_f32 v47, v38, v39
	global_store_dwordx4 v211, v[44:47], s[12:13] offset:256
	v_add_f32_e32 v40, v158, v159
	v_add_f32_e32 v41, v166, v167
	v_pk_mul_f32 v[32:33], v[32:33], v[212:213] op_sel_hi:[1,0]
	v_pk_mul_f32 v[34:35], v[34:35], v[212:213] op_sel_hi:[1,0]
	v_pk_mul_f32 v[24:25], v[24:25], v[212:213] op_sel_hi:[1,0]
	v_pk_mul_f32 v[26:27], v[26:27], v[212:213] op_sel_hi:[1,0]
	v_pk_mul_f32 v[28:29], v[28:29], v[212:213] op_sel_hi:[1,0]
	v_pk_mul_f32 v[30:31], v[30:31], v[212:213] op_sel_hi:[1,0]
	v_pk_mul_f32 v[20:21], v[20:21], v[212:213] op_sel_hi:[1,0]
	v_pk_mul_f32 v[22:23], v[22:23], v[212:213] op_sel_hi:[1,0]
	v_med3_f32 v158, v32, -4.0, 4.0
	v_med3_f32 v164, v34, -4.0, 4.0
	v_med3_f32 v170, v24, -4.0, 4.0
	v_med3_f32 v180, v26, -4.0, 4.0
	v_med3_f32 v159, v33, -4.0, 4.0
	v_med3_f32 v165, v35, -4.0, 4.0
	v_med3_f32 v171, v25, -4.0, 4.0
	v_med3_f32 v181, v27, -4.0, 4.0
	v_pk_mul_f32 v[160:161], v[158:159], v[158:159]
	v_pk_mul_f32 v[166:167], v[164:165], v[164:165]
	v_pk_mul_f32 v[172:173], v[170:171], v[170:171]
	v_pk_mul_f32 v[182:183], v[180:181], v[180:181]
	v_pk_fma_f32 v[160:161], v[160:161], s[72:73], -1.0 op_sel_hi:[1,0,0]
	v_pk_fma_f32 v[166:167], v[166:167], s[72:73], -1.0 op_sel_hi:[1,0,0]
	v_pk_fma_f32 v[172:173], v[172:173], s[72:73], -1.0 op_sel_hi:[1,0,0]
	v_pk_fma_f32 v[182:183], v[182:183], s[72:73], -1.0 op_sel_hi:[1,0,0]
	v_pk_fma_f32 v[162:163], v[160:161], s[74:75], v[198:199] op_sel_hi:[1,0,0]
	v_pk_fma_f32 v[168:169], v[166:167], s[74:75], v[198:199] op_sel_hi:[1,0,0]
	v_pk_fma_f32 v[178:179], v[172:173], s[74:75], v[198:199] op_sel_hi:[1,0,0]
	v_pk_fma_f32 v[184:185], v[182:183], s[74:75], v[198:199] op_sel_hi:[1,0,0]
	v_pk_fma_f32 v[162:163], v[160:161], v[162:163], s[2:3] op_sel_hi:[1,1,0]
	v_pk_fma_f32 v[168:169], v[166:167], v[168:169], s[2:3] op_sel_hi:[1,1,0]
	v_pk_fma_f32 v[178:179], v[172:173], v[178:179], s[2:3] op_sel_hi:[1,1,0]
	v_pk_fma_f32 v[184:185], v[182:183], v[184:185], s[2:3] op_sel_hi:[1,1,0]
	v_pk_fma_f32 v[162:163], v[160:161], v[162:163], s[28:29] op_sel_hi:[1,1,0]
	v_pk_fma_f32 v[168:169], v[166:167], v[168:169], s[28:29] op_sel_hi:[1,1,0]
	v_pk_fma_f32 v[178:179], v[172:173], v[178:179], s[28:29] op_sel_hi:[1,1,0]
	v_pk_fma_f32 v[184:185], v[182:183], v[184:185], s[28:29] op_sel_hi:[1,1,0]
	v_pk_fma_f32 v[162:163], v[160:161], v[162:163], s[30:31] op_sel_hi:[1,1,0]
	v_pk_fma_f32 v[168:169], v[166:167], v[168:169], s[30:31] op_sel_hi:[1,1,0]
	v_pk_fma_f32 v[178:179], v[172:173], v[178:179], s[30:31] op_sel_hi:[1,1,0]
	v_pk_fma_f32 v[184:185], v[182:183], v[184:185], s[30:31] op_sel_hi:[1,1,0]
	v_pk_fma_f32 v[162:163], v[160:161], v[162:163], s[48:49] op_sel_hi:[1,1,0]
	v_pk_fma_f32 v[168:169], v[166:167], v[168:169], s[48:49] op_sel_hi:[1,1,0]
	v_pk_fma_f32 v[178:179], v[172:173], v[178:179], s[48:49] op_sel_hi:[1,1,0]
	v_pk_fma_f32 v[184:185], v[182:183], v[184:185], s[48:49] op_sel_hi:[1,1,0]
	v_pk_fma_f32 v[162:163], v[160:161], v[162:163], s[50:51] op_sel_hi:[1,1,0]
	v_pk_fma_f32 v[168:169], v[166:167], v[168:169], s[50:51] op_sel_hi:[1,1,0]
	v_pk_fma_f32 v[178:179], v[172:173], v[178:179], s[50:51] op_sel_hi:[1,1,0]
	v_pk_fma_f32 v[184:185], v[182:183], v[184:185], s[50:51] op_sel_hi:[1,1,0]
	v_pk_fma_f32 v[162:163], v[160:161], v[162:163], s[52:53] op_sel_hi:[1,1,0]
	v_pk_fma_f32 v[168:169], v[166:167], v[168:169], s[52:53] op_sel_hi:[1,1,0]
	v_pk_fma_f32 v[178:179], v[172:173], v[178:179], s[52:53] op_sel_hi:[1,1,0]
	v_pk_fma_f32 v[184:185], v[182:183], v[184:185], s[52:53] op_sel_hi:[1,1,0]
	v_pk_fma_f32 v[160:161], v[160:161], v[162:163], s[54:55] op_sel_hi:[1,1,0]
	v_pk_fma_f32 v[166:167], v[166:167], v[168:169], s[54:55] op_sel_hi:[1,1,0]
	v_pk_fma_f32 v[172:173], v[172:173], v[178:179], s[54:55] op_sel_hi:[1,1,0]
	v_pk_fma_f32 v[182:183], v[182:183], v[184:185], s[54:55] op_sel_hi:[1,1,0]
	v_pk_fma_f32 v[158:159], v[158:159], v[160:161], 0.5 op_sel_hi:[1,1,0]
	v_pk_fma_f32 v[164:165], v[164:165], v[166:167], 0.5 op_sel_hi:[1,1,0]
	v_pk_fma_f32 v[170:171], v[170:171], v[172:173], 0.5 op_sel_hi:[1,1,0]
	v_pk_fma_f32 v[180:181], v[180:181], v[182:183], 0.5 op_sel_hi:[1,1,0]
	v_pk_mul_f32 v[32:33], v[32:33], v[158:159]
	v_pk_mul_f32 v[34:35], v[34:35], v[164:165]
	v_pk_mul_f32 v[24:25], v[24:25], v[170:171]
	v_pk_mul_f32 v[26:27], v[26:27], v[180:181]
	v_med3_f32 v158, v28, -4.0, 4.0
	v_med3_f32 v164, v30, -4.0, 4.0
	v_med3_f32 v170, v20, -4.0, 4.0
	v_med3_f32 v180, v22, -4.0, 4.0
	v_med3_f32 v159, v29, -4.0, 4.0
	v_med3_f32 v165, v31, -4.0, 4.0
	v_med3_f32 v171, v21, -4.0, 4.0
	v_med3_f32 v181, v23, -4.0, 4.0
	v_pk_mul_f32 v[160:161], v[158:159], v[158:159]
	v_pk_mul_f32 v[166:167], v[164:165], v[164:165]
	v_pk_mul_f32 v[172:173], v[170:171], v[170:171]
	v_pk_mul_f32 v[182:183], v[180:181], v[180:181]
	v_pk_fma_f32 v[160:161], v[160:161], s[72:73], -1.0 op_sel_hi:[1,0,0]
	v_pk_fma_f32 v[166:167], v[166:167], s[72:73], -1.0 op_sel_hi:[1,0,0]
	v_pk_fma_f32 v[172:173], v[172:173], s[72:73], -1.0 op_sel_hi:[1,0,0]
	v_pk_fma_f32 v[182:183], v[182:183], s[72:73], -1.0 op_sel_hi:[1,0,0]
	v_pk_fma_f32 v[162:163], v[160:161], s[74:75], v[198:199] op_sel_hi:[1,0,0]
	v_pk_fma_f32 v[168:169], v[166:167], s[74:75], v[198:199] op_sel_hi:[1,0,0]
	v_pk_fma_f32 v[178:179], v[172:173], s[74:75], v[198:199] op_sel_hi:[1,0,0]
	v_pk_fma_f32 v[184:185], v[182:183], s[74:75], v[198:199] op_sel_hi:[1,0,0]
	v_pk_fma_f32 v[162:163], v[160:161], v[162:163], s[2:3] op_sel_hi:[1,1,0]
	v_pk_fma_f32 v[168:169], v[166:167], v[168:169], s[2:3] op_sel_hi:[1,1,0]
	v_pk_fma_f32 v[178:179], v[172:173], v[178:179], s[2:3] op_sel_hi:[1,1,0]
	v_pk_fma_f32 v[184:185], v[182:183], v[184:185], s[2:3] op_sel_hi:[1,1,0]
	v_pk_fma_f32 v[162:163], v[160:161], v[162:163], s[28:29] op_sel_hi:[1,1,0]
	v_pk_fma_f32 v[168:169], v[166:167], v[168:169], s[28:29] op_sel_hi:[1,1,0]
	v_pk_fma_f32 v[178:179], v[172:173], v[178:179], s[28:29] op_sel_hi:[1,1,0]
	v_pk_fma_f32 v[184:185], v[182:183], v[184:185], s[28:29] op_sel_hi:[1,1,0]
	v_pk_fma_f32 v[162:163], v[160:161], v[162:163], s[30:31] op_sel_hi:[1,1,0]
	v_pk_fma_f32 v[168:169], v[166:167], v[168:169], s[30:31] op_sel_hi:[1,1,0]
	v_pk_fma_f32 v[178:179], v[172:173], v[178:179], s[30:31] op_sel_hi:[1,1,0]
	v_pk_fma_f32 v[184:185], v[182:183], v[184:185], s[30:31] op_sel_hi:[1,1,0]
	v_pk_fma_f32 v[162:163], v[160:161], v[162:163], s[48:49] op_sel_hi:[1,1,0]
	v_pk_fma_f32 v[168:169], v[166:167], v[168:169], s[48:49] op_sel_hi:[1,1,0]
	v_pk_fma_f32 v[178:179], v[172:173], v[178:179], s[48:49] op_sel_hi:[1,1,0]
	v_pk_fma_f32 v[184:185], v[182:183], v[184:185], s[48:49] op_sel_hi:[1,1,0]
	v_pk_fma_f32 v[162:163], v[160:161], v[162:163], s[50:51] op_sel_hi:[1,1,0]
	v_pk_fma_f32 v[168:169], v[166:167], v[168:169], s[50:51] op_sel_hi:[1,1,0]
	v_pk_fma_f32 v[178:179], v[172:173], v[178:179], s[50:51] op_sel_hi:[1,1,0]
	v_pk_fma_f32 v[184:185], v[182:183], v[184:185], s[50:51] op_sel_hi:[1,1,0]
	v_pk_fma_f32 v[162:163], v[160:161], v[162:163], s[52:53] op_sel_hi:[1,1,0]
	v_pk_fma_f32 v[168:169], v[166:167], v[168:169], s[52:53] op_sel_hi:[1,1,0]
	v_pk_fma_f32 v[178:179], v[172:173], v[178:179], s[52:53] op_sel_hi:[1,1,0]
	v_pk_fma_f32 v[184:185], v[182:183], v[184:185], s[52:53] op_sel_hi:[1,1,0]
	v_pk_fma_f32 v[160:161], v[160:161], v[162:163], s[54:55] op_sel_hi:[1,1,0]
	v_pk_fma_f32 v[166:167], v[166:167], v[168:169], s[54:55] op_sel_hi:[1,1,0]
	v_pk_fma_f32 v[172:173], v[172:173], v[178:179], s[54:55] op_sel_hi:[1,1,0]
	v_pk_fma_f32 v[182:183], v[182:183], v[184:185], s[54:55] op_sel_hi:[1,1,0]
	v_pk_fma_f32 v[158:159], v[158:159], v[160:161], 0.5 op_sel_hi:[1,1,0]
	v_pk_fma_f32 v[164:165], v[164:165], v[166:167], 0.5 op_sel_hi:[1,1,0]
	v_pk_fma_f32 v[170:171], v[170:171], v[172:173], 0.5 op_sel_hi:[1,1,0]
	v_pk_fma_f32 v[180:181], v[180:181], v[182:183], 0.5 op_sel_hi:[1,1,0]
	v_pk_mul_f32 v[28:29], v[28:29], v[158:159]
	v_pk_mul_f32 v[30:31], v[30:31], v[164:165]
	v_pk_mul_f32 v[20:21], v[20:21], v[170:171]
	v_pk_mul_f32 v[22:23], v[22:23], v[180:181]
	v_pk_add_f32 v[158:159], v[32:33], v[34:35]
	v_pk_add_f32 v[160:161], v[24:25], v[26:27]
	v_pk_add_f32 v[162:163], v[28:29], v[30:31]
	v_pk_add_f32 v[164:165], v[20:21], v[22:23]
	v_pk_mul_f32 v[166:167], v[32:33], v[32:33]
	v_pk_mul_f32 v[168:169], v[24:25], v[24:25]
	v_pk_mul_f32 v[170:171], v[28:29], v[28:29]
	v_pk_mul_f32 v[172:173], v[20:21], v[20:21]
	v_pk_fma_f32 v[166:167], v[34:35], v[34:35], v[166:167]
	v_pk_fma_f32 v[168:169], v[26:27], v[26:27], v[168:169]
	v_pk_fma_f32 v[170:171], v[30:31], v[30:31], v[170:171]
	v_pk_fma_f32 v[172:173], v[22:23], v[22:23], v[172:173]
	v_pk_add_f32 v[158:159], v[158:159], v[160:161]
	v_pk_add_f32 v[162:163], v[162:163], v[164:165]
	v_pk_add_f32 v[166:167], v[166:167], v[168:169]
	v_pk_add_f32 v[170:171], v[170:171], v[172:173]
	v_pk_add_f32 v[158:159], v[158:159], v[162:163]
	v_pk_add_f32 v[166:167], v[166:167], v[170:171]
	v_cvt_pk_bf16_f32 v32, v32, v33
	v_cvt_pk_bf16_f32 v33, v34, v35
	v_cvt_pk_bf16_f32 v34, v24, v25
	v_cvt_pk_bf16_f32 v35, v26, v27
	global_store_dwordx4 v213, v[32:35], s[12:13]
	v_cvt_pk_bf16_f32 v28, v28, v29
	v_cvt_pk_bf16_f32 v29, v30, v31
	v_cvt_pk_bf16_f32 v30, v20, v21
	v_cvt_pk_bf16_f32 v31, v22, v23
	global_store_dwordx4 v213, v[28:31], s[12:13] offset:256
	v_add_f32_e32 v24, v158, v159
	v_add_f32_e32 v25, v166, v167
	v_pk_mul_f32 v[16:17], v[16:17], v[214:215] op_sel_hi:[1,0]
	v_pk_mul_f32 v[18:19], v[18:19], v[214:215] op_sel_hi:[1,0]
	v_pk_mul_f32 v[8:9], v[8:9], v[214:215] op_sel_hi:[1,0]
	v_pk_mul_f32 v[10:11], v[10:11], v[214:215] op_sel_hi:[1,0]
	v_pk_mul_f32 v[12:13], v[12:13], v[214:215] op_sel_hi:[1,0]
	v_pk_mul_f32 v[14:15], v[14:15], v[214:215] op_sel_hi:[1,0]
	v_pk_mul_f32 v[4:5], v[4:5], v[214:215] op_sel_hi:[1,0]
	v_pk_mul_f32 v[6:7], v[6:7], v[214:215] op_sel_hi:[1,0]
	v_med3_f32 v158, v16, -4.0, 4.0
	v_med3_f32 v164, v18, -4.0, 4.0
	v_med3_f32 v170, v8, -4.0, 4.0
	v_med3_f32 v180, v10, -4.0, 4.0
	v_med3_f32 v159, v17, -4.0, 4.0
	v_med3_f32 v165, v19, -4.0, 4.0
	v_med3_f32 v171, v9, -4.0, 4.0
	v_med3_f32 v181, v11, -4.0, 4.0
	v_pk_mul_f32 v[160:161], v[158:159], v[158:159]
	v_pk_mul_f32 v[166:167], v[164:165], v[164:165]
	v_pk_mul_f32 v[172:173], v[170:171], v[170:171]
	v_pk_mul_f32 v[182:183], v[180:181], v[180:181]
	v_pk_fma_f32 v[160:161], v[160:161], s[72:73], -1.0 op_sel_hi:[1,0,0]
	v_pk_fma_f32 v[166:167], v[166:167], s[72:73], -1.0 op_sel_hi:[1,0,0]
	v_pk_fma_f32 v[172:173], v[172:173], s[72:73], -1.0 op_sel_hi:[1,0,0]
	v_pk_fma_f32 v[182:183], v[182:183], s[72:73], -1.0 op_sel_hi:[1,0,0]
	v_pk_fma_f32 v[162:163], v[160:161], s[74:75], v[198:199] op_sel_hi:[1,0,0]
	v_pk_fma_f32 v[168:169], v[166:167], s[74:75], v[198:199] op_sel_hi:[1,0,0]
	v_pk_fma_f32 v[178:179], v[172:173], s[74:75], v[198:199] op_sel_hi:[1,0,0]
	v_pk_fma_f32 v[184:185], v[182:183], s[74:75], v[198:199] op_sel_hi:[1,0,0]
	v_pk_fma_f32 v[162:163], v[160:161], v[162:163], s[2:3] op_sel_hi:[1,1,0]
	v_pk_fma_f32 v[168:169], v[166:167], v[168:169], s[2:3] op_sel_hi:[1,1,0]
	v_pk_fma_f32 v[178:179], v[172:173], v[178:179], s[2:3] op_sel_hi:[1,1,0]
	v_pk_fma_f32 v[184:185], v[182:183], v[184:185], s[2:3] op_sel_hi:[1,1,0]
	v_pk_fma_f32 v[162:163], v[160:161], v[162:163], s[28:29] op_sel_hi:[1,1,0]
	v_pk_fma_f32 v[168:169], v[166:167], v[168:169], s[28:29] op_sel_hi:[1,1,0]
	v_pk_fma_f32 v[178:179], v[172:173], v[178:179], s[28:29] op_sel_hi:[1,1,0]
	v_pk_fma_f32 v[184:185], v[182:183], v[184:185], s[28:29] op_sel_hi:[1,1,0]
	v_pk_fma_f32 v[162:163], v[160:161], v[162:163], s[30:31] op_sel_hi:[1,1,0]
	v_pk_fma_f32 v[168:169], v[166:167], v[168:169], s[30:31] op_sel_hi:[1,1,0]
	v_pk_fma_f32 v[178:179], v[172:173], v[178:179], s[30:31] op_sel_hi:[1,1,0]
	v_pk_fma_f32 v[184:185], v[182:183], v[184:185], s[30:31] op_sel_hi:[1,1,0]
	v_pk_fma_f32 v[162:163], v[160:161], v[162:163], s[48:49] op_sel_hi:[1,1,0]
	v_pk_fma_f32 v[168:169], v[166:167], v[168:169], s[48:49] op_sel_hi:[1,1,0]
	v_pk_fma_f32 v[178:179], v[172:173], v[178:179], s[48:49] op_sel_hi:[1,1,0]
	v_pk_fma_f32 v[184:185], v[182:183], v[184:185], s[48:49] op_sel_hi:[1,1,0]
	v_pk_fma_f32 v[162:163], v[160:161], v[162:163], s[50:51] op_sel_hi:[1,1,0]
	v_pk_fma_f32 v[168:169], v[166:167], v[168:169], s[50:51] op_sel_hi:[1,1,0]
	v_pk_fma_f32 v[178:179], v[172:173], v[178:179], s[50:51] op_sel_hi:[1,1,0]
	v_pk_fma_f32 v[184:185], v[182:183], v[184:185], s[50:51] op_sel_hi:[1,1,0]
	v_pk_fma_f32 v[162:163], v[160:161], v[162:163], s[52:53] op_sel_hi:[1,1,0]
	v_pk_fma_f32 v[168:169], v[166:167], v[168:169], s[52:53] op_sel_hi:[1,1,0]
	v_pk_fma_f32 v[178:179], v[172:173], v[178:179], s[52:53] op_sel_hi:[1,1,0]
	v_pk_fma_f32 v[184:185], v[182:183], v[184:185], s[52:53] op_sel_hi:[1,1,0]
	v_pk_fma_f32 v[160:161], v[160:161], v[162:163], s[54:55] op_sel_hi:[1,1,0]
	v_pk_fma_f32 v[166:167], v[166:167], v[168:169], s[54:55] op_sel_hi:[1,1,0]
	v_pk_fma_f32 v[172:173], v[172:173], v[178:179], s[54:55] op_sel_hi:[1,1,0]
	v_pk_fma_f32 v[182:183], v[182:183], v[184:185], s[54:55] op_sel_hi:[1,1,0]
	v_pk_fma_f32 v[158:159], v[158:159], v[160:161], 0.5 op_sel_hi:[1,1,0]
	v_pk_fma_f32 v[164:165], v[164:165], v[166:167], 0.5 op_sel_hi:[1,1,0]
	v_pk_fma_f32 v[170:171], v[170:171], v[172:173], 0.5 op_sel_hi:[1,1,0]
	v_pk_fma_f32 v[180:181], v[180:181], v[182:183], 0.5 op_sel_hi:[1,1,0]
	v_pk_mul_f32 v[16:17], v[16:17], v[158:159]
	v_pk_mul_f32 v[18:19], v[18:19], v[164:165]
	v_pk_mul_f32 v[8:9], v[8:9], v[170:171]
	v_pk_mul_f32 v[10:11], v[10:11], v[180:181]
	v_med3_f32 v158, v12, -4.0, 4.0
	v_med3_f32 v164, v14, -4.0, 4.0
	v_med3_f32 v170, v4, -4.0, 4.0
	v_med3_f32 v180, v6, -4.0, 4.0
	v_med3_f32 v159, v13, -4.0, 4.0
	v_med3_f32 v165, v15, -4.0, 4.0
	v_med3_f32 v171, v5, -4.0, 4.0
	v_med3_f32 v181, v7, -4.0, 4.0
	v_pk_mul_f32 v[160:161], v[158:159], v[158:159]
	v_pk_mul_f32 v[166:167], v[164:165], v[164:165]
	v_pk_mul_f32 v[172:173], v[170:171], v[170:171]
	v_pk_mul_f32 v[182:183], v[180:181], v[180:181]
	v_pk_fma_f32 v[160:161], v[160:161], s[72:73], -1.0 op_sel_hi:[1,0,0]
	v_pk_fma_f32 v[166:167], v[166:167], s[72:73], -1.0 op_sel_hi:[1,0,0]
	v_pk_fma_f32 v[172:173], v[172:173], s[72:73], -1.0 op_sel_hi:[1,0,0]
	v_pk_fma_f32 v[182:183], v[182:183], s[72:73], -1.0 op_sel_hi:[1,0,0]
	v_pk_fma_f32 v[162:163], v[160:161], s[74:75], v[198:199] op_sel_hi:[1,0,0]
	v_pk_fma_f32 v[168:169], v[166:167], s[74:75], v[198:199] op_sel_hi:[1,0,0]
	v_pk_fma_f32 v[178:179], v[172:173], s[74:75], v[198:199] op_sel_hi:[1,0,0]
	v_pk_fma_f32 v[184:185], v[182:183], s[74:75], v[198:199] op_sel_hi:[1,0,0]
	v_pk_fma_f32 v[162:163], v[160:161], v[162:163], s[2:3] op_sel_hi:[1,1,0]
	v_pk_fma_f32 v[168:169], v[166:167], v[168:169], s[2:3] op_sel_hi:[1,1,0]
	v_pk_fma_f32 v[178:179], v[172:173], v[178:179], s[2:3] op_sel_hi:[1,1,0]
	v_pk_fma_f32 v[184:185], v[182:183], v[184:185], s[2:3] op_sel_hi:[1,1,0]
	v_pk_fma_f32 v[162:163], v[160:161], v[162:163], s[28:29] op_sel_hi:[1,1,0]
	v_pk_fma_f32 v[168:169], v[166:167], v[168:169], s[28:29] op_sel_hi:[1,1,0]
	v_pk_fma_f32 v[178:179], v[172:173], v[178:179], s[28:29] op_sel_hi:[1,1,0]
	v_pk_fma_f32 v[184:185], v[182:183], v[184:185], s[28:29] op_sel_hi:[1,1,0]
	v_pk_fma_f32 v[162:163], v[160:161], v[162:163], s[30:31] op_sel_hi:[1,1,0]
	v_pk_fma_f32 v[168:169], v[166:167], v[168:169], s[30:31] op_sel_hi:[1,1,0]
	v_pk_fma_f32 v[178:179], v[172:173], v[178:179], s[30:31] op_sel_hi:[1,1,0]
	v_pk_fma_f32 v[184:185], v[182:183], v[184:185], s[30:31] op_sel_hi:[1,1,0]
	v_pk_fma_f32 v[162:163], v[160:161], v[162:163], s[48:49] op_sel_hi:[1,1,0]
	v_pk_fma_f32 v[168:169], v[166:167], v[168:169], s[48:49] op_sel_hi:[1,1,0]
	v_pk_fma_f32 v[178:179], v[172:173], v[178:179], s[48:49] op_sel_hi:[1,1,0]
	v_pk_fma_f32 v[184:185], v[182:183], v[184:185], s[48:49] op_sel_hi:[1,1,0]
	v_pk_fma_f32 v[162:163], v[160:161], v[162:163], s[50:51] op_sel_hi:[1,1,0]
	v_pk_fma_f32 v[168:169], v[166:167], v[168:169], s[50:51] op_sel_hi:[1,1,0]
	v_pk_fma_f32 v[178:179], v[172:173], v[178:179], s[50:51] op_sel_hi:[1,1,0]
	v_pk_fma_f32 v[184:185], v[182:183], v[184:185], s[50:51] op_sel_hi:[1,1,0]
	v_pk_fma_f32 v[162:163], v[160:161], v[162:163], s[52:53] op_sel_hi:[1,1,0]
	v_pk_fma_f32 v[168:169], v[166:167], v[168:169], s[52:53] op_sel_hi:[1,1,0]
	v_pk_fma_f32 v[178:179], v[172:173], v[178:179], s[52:53] op_sel_hi:[1,1,0]
	v_pk_fma_f32 v[184:185], v[182:183], v[184:185], s[52:53] op_sel_hi:[1,1,0]
	v_pk_fma_f32 v[160:161], v[160:161], v[162:163], s[54:55] op_sel_hi:[1,1,0]
	v_pk_fma_f32 v[166:167], v[166:167], v[168:169], s[54:55] op_sel_hi:[1,1,0]
	v_pk_fma_f32 v[172:173], v[172:173], v[178:179], s[54:55] op_sel_hi:[1,1,0]
	v_pk_fma_f32 v[182:183], v[182:183], v[184:185], s[54:55] op_sel_hi:[1,1,0]
	v_pk_fma_f32 v[158:159], v[158:159], v[160:161], 0.5 op_sel_hi:[1,1,0]
	v_pk_fma_f32 v[164:165], v[164:165], v[166:167], 0.5 op_sel_hi:[1,1,0]
	v_pk_fma_f32 v[170:171], v[170:171], v[172:173], 0.5 op_sel_hi:[1,1,0]
	v_pk_fma_f32 v[180:181], v[180:181], v[182:183], 0.5 op_sel_hi:[1,1,0]
	v_pk_mul_f32 v[12:13], v[12:13], v[158:159]
	v_pk_mul_f32 v[14:15], v[14:15], v[164:165]
	v_pk_mul_f32 v[4:5], v[4:5], v[170:171]
	v_pk_mul_f32 v[6:7], v[6:7], v[180:181]
	v_pk_add_f32 v[158:159], v[16:17], v[18:19]
	v_pk_add_f32 v[160:161], v[8:9], v[10:11]
	v_pk_add_f32 v[162:163], v[12:13], v[14:15]
	v_pk_add_f32 v[164:165], v[4:5], v[6:7]
	v_pk_mul_f32 v[166:167], v[16:17], v[16:17]
	v_pk_mul_f32 v[168:169], v[8:9], v[8:9]
	v_pk_mul_f32 v[170:171], v[12:13], v[12:13]
	v_pk_mul_f32 v[172:173], v[4:5], v[4:5]
	v_pk_fma_f32 v[166:167], v[18:19], v[18:19], v[166:167]
	v_pk_fma_f32 v[168:169], v[10:11], v[10:11], v[168:169]
	v_pk_fma_f32 v[170:171], v[14:15], v[14:15], v[170:171]
	v_pk_fma_f32 v[172:173], v[6:7], v[6:7], v[172:173]
	v_pk_add_f32 v[158:159], v[158:159], v[160:161]
	v_pk_add_f32 v[162:163], v[162:163], v[164:165]
	v_pk_add_f32 v[166:167], v[166:167], v[168:169]
	v_pk_add_f32 v[170:171], v[170:171], v[172:173]
	v_pk_add_f32 v[158:159], v[158:159], v[162:163]
	v_pk_add_f32 v[166:167], v[166:167], v[170:171]
	v_cvt_pk_bf16_f32 v16, v16, v17
	v_cvt_pk_bf16_f32 v17, v18, v19
	v_cvt_pk_bf16_f32 v18, v8, v9
	v_cvt_pk_bf16_f32 v19, v10, v11
	global_store_dwordx4 v215, v[16:19], s[12:13]
	v_cvt_pk_bf16_f32 v12, v12, v13
	v_cvt_pk_bf16_f32 v13, v14, v15
	v_cvt_pk_bf16_f32 v14, v4, v5
	v_cvt_pk_bf16_f32 v15, v6, v7
	global_store_dwordx4 v215, v[12:15], s[12:13] offset:256
	v_add_f32_e32 v8, v158, v159
	v_add_f32_e32 v9, v166, v167
	ds_bpermute_b32 v122, v146, v120
	ds_bpermute_b32 v123, v146, v121
	ds_bpermute_b32 v106, v146, v104
	ds_bpermute_b32 v107, v146, v105
	ds_bpermute_b32 v90, v146, v88
	ds_bpermute_b32 v91, v146, v89
	ds_bpermute_b32 v74, v146, v72
	ds_bpermute_b32 v75, v146, v73
	ds_bpermute_b32 v58, v146, v56
	ds_bpermute_b32 v59, v146, v57
	ds_bpermute_b32 v42, v146, v40
	ds_bpermute_b32 v43, v146, v41
	ds_bpermute_b32 v26, v146, v24
	ds_bpermute_b32 v27, v146, v25
	ds_bpermute_b32 v10, v146, v8
	ds_bpermute_b32 v11, v146, v9
	s_waitcnt lgkmcnt(0)
	v_pk_add_f32 v[120:121], v[120:121], v[122:123]
	v_pk_add_f32 v[104:105], v[104:105], v[106:107]
	v_pk_add_f32 v[88:89], v[88:89], v[90:91]
	v_pk_add_f32 v[72:73], v[72:73], v[74:75]
	v_pk_add_f32 v[56:57], v[56:57], v[58:59]
	v_pk_add_f32 v[40:41], v[40:41], v[42:43]
	v_pk_add_f32 v[24:25], v[24:25], v[26:27]
	v_pk_add_f32 v[8:9], v[8:9], v[10:11]
	ds_bpermute_b32 v122, v147, v120
	ds_bpermute_b32 v123, v147, v121
	ds_bpermute_b32 v106, v147, v104
	ds_bpermute_b32 v107, v147, v105
	ds_bpermute_b32 v90, v147, v88
	ds_bpermute_b32 v91, v147, v89
	ds_bpermute_b32 v74, v147, v72
	ds_bpermute_b32 v75, v147, v73
	ds_bpermute_b32 v58, v147, v56
	ds_bpermute_b32 v59, v147, v57
	ds_bpermute_b32 v42, v147, v40
	ds_bpermute_b32 v43, v147, v41
	ds_bpermute_b32 v26, v147, v24
	ds_bpermute_b32 v27, v147, v25
	ds_bpermute_b32 v10, v147, v8
	ds_bpermute_b32 v11, v147, v9
	s_waitcnt lgkmcnt(0)
	v_pk_add_f32 v[120:121], v[120:121], v[122:123]
	v_pk_add_f32 v[104:105], v[104:105], v[106:107]
	v_pk_add_f32 v[88:89], v[88:89], v[90:91]
	v_pk_add_f32 v[72:73], v[72:73], v[74:75]
	v_pk_add_f32 v[56:57], v[56:57], v[58:59]
	v_pk_add_f32 v[40:41], v[40:41], v[42:43]
	v_pk_add_f32 v[24:25], v[24:25], v[26:27]
	v_pk_add_f32 v[8:9], v[8:9], v[10:11]
	s_and_saveexec_b64 s[0:1], s[4:5]
	global_store_dwordx2 v216, v[120:121], s[14:15]
	global_store_dwordx2 v217, v[104:105], s[14:15]
	global_store_dwordx2 v218, v[88:89], s[14:15]
	global_store_dwordx2 v219, v[72:73], s[14:15]
	global_store_dwordx2 v220, v[56:57], s[14:15]
	global_store_dwordx2 v221, v[40:41], s[14:15]
	global_store_dwordx2 v186, v[24:25], s[14:15]
	global_store_dwordx2 v187, v[8:9], s[14:15]
